# gelu+LayerNorm class: 16 scalar sigmoid-factor chains per region replaced by 8 packed chains (results in hipcc's registers), on top of rope peephole
# speedup vs baseline: 1.0042x; 1.0042x over previous
.LBB0_227:
	s_cmp_lt_i32 s40, 64
	s_cselect_b64 s[38:39], -1, 0
	s_lshl_b32 s29, s40, 8
	s_and_b32 s27, s29, 0x1f00
	s_sub_i32 s8, s40, 64
	s_ashr_i32 s9, s40, 5
	s_addk_i32 s27, 0x100
	s_cmp_gt_i32 s40, 63
	s_cselect_b32 s44, s8, s9
	s_cselect_b32 s27, 0, s27
	v_add_u32_e32 v204, s29, v171
	s_mov_b64 s[40:41], -1
	s_mov_b64 s[8:9], 0
	s_cmp_lt_i32 s13, 1
	s_mov_b64 s[46:47], 0
	s_cbranch_scc1 .LBB0_231
	s_cmp_eq_u32 s13, 1
	s_mov_b64 s[46:47], -1
	s_cbranch_scc0 .LBB0_230
	s_mov_b32 s100, 0x3d372713
	s_mov_b32 s101, 0x3f4c422a
	v_mov_b32_e32 v248, 0xc038aa3b
	v_pk_mul_f32 v[238:239], v[162:163], s[100:101] op_sel_hi:[1,0]
	v_pk_mul_f32 v[238:239], v[162:163], v[238:239]
	v_pk_fma_f32 v[238:239], v[162:163], v[238:239], v[162:163]
	v_pk_mul_f32 v[238:239], v[238:239], s[100:101] op_sel:[0,1] op_sel_hi:[1,1]
	v_pk_mul_f32 v[238:239], v[238:239], v[248:249] op_sel_hi:[1,0]
	v_exp_f32_e32 v238, v238
	v_exp_f32_e32 v239, v239
	s_nop 0
	v_pk_add_f32 v[238:239], v[238:239], 1.0 op_sel_hi:[1,0]
	v_rcp_f32_e32 v156, v238
	v_rcp_f32_e32 v157, v239
	v_pk_mul_f32 v[240:241], v[164:165], s[100:101] op_sel_hi:[1,0]
	v_pk_mul_f32 v[240:241], v[164:165], v[240:241]
	v_pk_fma_f32 v[240:241], v[164:165], v[240:241], v[164:165]
	v_pk_mul_f32 v[240:241], v[240:241], s[100:101] op_sel:[0,1] op_sel_hi:[1,1]
	v_pk_mul_f32 v[240:241], v[240:241], v[248:249] op_sel_hi:[1,0]
	v_exp_f32_e32 v240, v240
	v_exp_f32_e32 v241, v241
	s_nop 0
	v_pk_add_f32 v[240:241], v[240:241], 1.0 op_sel_hi:[1,0]
	v_rcp_f32_e32 v158, v240
	v_rcp_f32_e32 v159, v241
	v_pk_mul_f32 v[242:243], v[142:143], s[100:101] op_sel_hi:[1,0]
	v_pk_mul_f32 v[242:243], v[142:143], v[242:243]
	v_pk_fma_f32 v[242:243], v[142:143], v[242:243], v[142:143]
	v_pk_mul_f32 v[242:243], v[242:243], s[100:101] op_sel:[0,1] op_sel_hi:[1,1]
	v_pk_mul_f32 v[242:243], v[242:243], v[248:249] op_sel_hi:[1,0]
	v_exp_f32_e32 v242, v242
	v_exp_f32_e32 v243, v243
	s_nop 0
	v_pk_add_f32 v[242:243], v[242:243], 1.0 op_sel_hi:[1,0]
	v_rcp_f32_e32 v160, v242
	v_rcp_f32_e32 v161, v243
	v_pk_mul_f32 v[244:245], v[144:145], s[100:101] op_sel_hi:[1,0]
	v_pk_mul_f32 v[244:245], v[144:145], v[244:245]
	v_pk_fma_f32 v[244:245], v[144:145], v[244:245], v[144:145]
	v_pk_mul_f32 v[244:245], v[244:245], s[100:101] op_sel:[0,1] op_sel_hi:[1,1]
	v_pk_mul_f32 v[244:245], v[244:245], v[248:249] op_sel_hi:[1,0]
	v_exp_f32_e32 v244, v244
	v_exp_f32_e32 v245, v245
	s_nop 0
	v_pk_add_f32 v[244:245], v[244:245], 1.0 op_sel_hi:[1,0]
	v_rcp_f32_e32 v205, v244
	v_rcp_f32_e32 v206, v245
	v_fma_f32 v152, v162, v156, 0
	v_pk_mul_f32 v[246:247], v[138:139], s[100:101] op_sel_hi:[1,0]
	v_pk_mul_f32 v[246:247], v[138:139], v[246:247]
	v_pk_fma_f32 v[246:247], v[138:139], v[246:247], v[138:139]
	v_pk_mul_f32 v[246:247], v[246:247], s[100:101] op_sel:[0,1] op_sel_hi:[1,1]
	v_pk_mul_f32 v[246:247], v[246:247], v[248:249] op_sel_hi:[1,0]
	v_exp_f32_e32 v246, v246
	v_exp_f32_e32 v247, v247
	s_nop 0
	v_pk_add_f32 v[246:247], v[246:247], 1.0 op_sel_hi:[1,0]
	v_rcp_f32_e32 v146, v246
	v_fmac_f32_e32 v152, v163, v157
	v_fmac_f32_e32 v152, v164, v158
	v_fmac_f32_e32 v152, v165, v159
	v_rcp_f32_e32 v147, v247
	v_fmac_f32_e32 v152, v142, v160
	v_fmac_f32_e32 v152, v143, v161
	v_fmac_f32_e32 v152, v144, v205
	v_fmac_f32_e32 v152, v145, v206
	v_pk_mul_f32 v[238:239], v[140:141], s[100:101] op_sel_hi:[1,0]
	v_pk_mul_f32 v[238:239], v[140:141], v[238:239]
	v_pk_fma_f32 v[238:239], v[140:141], v[238:239], v[140:141]
	v_pk_mul_f32 v[238:239], v[238:239], s[100:101] op_sel:[0,1] op_sel_hi:[1,1]
	v_pk_mul_f32 v[238:239], v[238:239], v[248:249] op_sel_hi:[1,0]
	v_exp_f32_e32 v238, v238
	v_exp_f32_e32 v239, v239
	s_nop 0
	v_pk_add_f32 v[238:239], v[238:239], 1.0 op_sel_hi:[1,0]
	v_rcp_f32_e32 v148, v238
	v_pk_mul_f32 v[150:151], v[138:139], v[146:147]
	v_rcp_f32_e32 v149, v239
	v_add_f32_e32 v0, v152, v150
	v_add_f32_e32 v0, v151, v0
	v_pk_mul_f32 v[150:151], v[140:141], v[148:149]
	v_add_f32_e32 v0, v150, v0
	v_add_f32_e32 v0, v151, v0
	v_pk_mul_f32 v[240:241], v[134:135], s[100:101] op_sel_hi:[1,0]
	v_pk_mul_f32 v[240:241], v[134:135], v[240:241]
	v_pk_fma_f32 v[240:241], v[134:135], v[240:241], v[134:135]
	v_pk_mul_f32 v[240:241], v[240:241], s[100:101] op_sel:[0,1] op_sel_hi:[1,1]
	v_pk_mul_f32 v[240:241], v[240:241], v[248:249] op_sel_hi:[1,0]
	v_exp_f32_e32 v240, v240
	v_exp_f32_e32 v241, v241
	s_nop 0
	v_pk_add_f32 v[240:241], v[240:241], 1.0 op_sel_hi:[1,0]
	v_rcp_f32_e32 v150, v240
	v_rcp_f32_e32 v151, v241
	v_pk_mul_f32 v[242:243], v[136:137], s[100:101] op_sel_hi:[1,0]
	v_pk_mul_f32 v[242:243], v[136:137], v[242:243]
	v_pk_fma_f32 v[242:243], v[136:137], v[242:243], v[136:137]
	v_pk_mul_f32 v[242:243], v[242:243], s[100:101] op_sel:[0,1] op_sel_hi:[1,1]
	v_pk_mul_f32 v[242:243], v[242:243], v[248:249] op_sel_hi:[1,0]
	v_exp_f32_e32 v242, v242
	v_exp_f32_e32 v243, v243
	s_nop 0
	v_pk_add_f32 v[242:243], v[242:243], 1.0 op_sel_hi:[1,0]
	v_rcp_f32_e32 v152, v242
	v_rcp_f32_e32 v153, v243
	v_pk_mul_f32 v[154:155], v[134:135], v[150:151]
	s_mov_b64 s[46:47], 0
	v_add_f32_e32 v0, v154, v0
	v_add_f32_e32 v0, v155, v0
	v_pk_mul_f32 v[154:155], v[136:137], v[152:153]
	s_nop 0
	v_add_f32_e32 v0, v154, v0
	v_add_f32_e32 v0, v155, v0
	v_and_b32_e32 v155, 64, v224
	v_xor_b32_e32 v154, 16, v224
	v_add_u32_e32 v155, 64, v155
	v_cmp_lt_i32_e32 vcc, v154, v155
	s_nop 1
	v_cndmask_b32_e32 v154, v224, v154, vcc
	v_lshlrev_b32_e32 v207, 2, v154
	ds_bpermute_b32 v154, v207, v0
	s_waitcnt lgkmcnt(0)
	v_add_f32_e32 v0, v0, v154
	v_xor_b32_e32 v154, 32, v224
	v_cmp_lt_i32_e32 vcc, v154, v155
	s_nop 1
	v_cndmask_b32_e32 v154, v224, v154, vcc
	v_lshlrev_b32_e32 v214, 2, v154
	ds_bpermute_b32 v154, v214, v0
	s_waitcnt lgkmcnt(0)
	v_add_f32_e32 v0, v0, v154
	v_mul_f32_e32 v0, 0x3c800000, v0
	v_fma_f32 v216, v163, v157, -v0
	v_fma_f32 v215, v162, v156, -v0
	v_mul_f32_e32 v156, v216, v216
	v_fmac_f32_e32 v156, v215, v215
	v_fma_f32 v158, v164, v158, -v0
	v_fmac_f32_e32 v156, v158, v158
	v_fma_f32 v159, v165, v159, -v0
	v_fmac_f32_e32 v156, v159, v159
	v_fma_f32 v160, v142, v160, -v0
	v_fmac_f32_e32 v156, v160, v160
	v_fma_f32 v161, v143, v161, -v0
	v_fmac_f32_e32 v156, v161, v161
	v_fma_f32 v217, v144, v205, -v0
	v_fmac_f32_e32 v156, v217, v217
	v_fma_f32 v206, v145, v206, -v0
	v_pk_fma_f32 v[154:155], v[138:139], v[146:147], v[0:1] op_sel_hi:[1,1,0] neg_lo:[0,0,1] neg_hi:[0,0,1]
	v_fmac_f32_e32 v156, v206, v206
	v_pk_mul_f32 v[146:147], v[154:155], v[154:155]
	v_pk_fma_f32 v[150:151], v[134:135], v[150:151], v[0:1] op_sel_hi:[1,1,0] neg_lo:[0,0,1] neg_hi:[0,0,1]
	v_add_f32_e32 v146, v146, v156
	v_pk_fma_f32 v[156:157], v[140:141], v[148:149], v[0:1] op_sel_hi:[1,1,0] neg_lo:[0,0,1] neg_hi:[0,0,1]
	v_add_f32_e32 v205, v147, v146
	v_pk_mul_f32 v[146:147], v[156:157], v[156:157]
	v_pk_fma_f32 v[152:153], v[136:137], v[152:153], v[0:1] op_sel_hi:[1,1,0] neg_lo:[0,0,1] neg_hi:[0,0,1]
	v_add_f32_e32 v146, v146, v205
	v_add_f32_e32 v148, v147, v146
	v_pk_mul_f32 v[146:147], v[150:151], v[150:151]
	v_ashrrev_i32_e32 v205, 31, v204
	v_add_f32_e32 v146, v146, v148
	v_add_f32_e32 v148, v147, v146
	v_pk_mul_f32 v[146:147], v[152:153], v[152:153]
	s_nop 0
	v_add_f32_e32 v0, v146, v148
	v_add_f32_e32 v0, v147, v0
	ds_bpermute_b32 v146, v207, v0
	s_waitcnt lgkmcnt(0)
	v_add_f32_e32 v0, v0, v146
	ds_bpermute_b32 v146, v214, v0
	s_waitcnt lgkmcnt(0)
	v_add_f32_e32 v0, v0, v146
	v_fmamk_f32 v0, v0, 0x3c800000, v222
	v_mul_f32_e32 v146, 0x4b800000, v0
	v_cmp_gt_f32_e32 vcc, s78, v0
	s_nop 1
	v_cndmask_b32_e32 v0, v0, v146, vcc
	v_rsq_f32_e32 v0, v0
	s_nop 0
	v_mul_f32_e32 v146, 0x45800000, v0
	v_cndmask_b32_e32 v0, v0, v146, vcc
	v_lshlrev_b64 v[146:147], 9, v[204:205]
	v_mul_f32_e32 v148, v215, v0
	v_mul_f32_e32 v149, v216, v0
	v_mul_f32_e32 v205, v158, v0
	v_mul_f32_e32 v207, v159, v0
	v_mul_f32_e32 v160, v160, v0
	v_mul_f32_e32 v161, v161, v0
	v_mul_f32_e32 v214, v217, v0
	v_mul_f32_e32 v206, v206, v0
	v_lshl_add_u64 v[158:159], v[196:197], 0, v[146:147]
	v_cvt_pk_bf16_f32 v146, v148, v149
	v_cvt_pk_bf16_f32 v147, v205, v207
	v_cvt_pk_bf16_f32 v148, v160, v161
	v_cvt_pk_bf16_f32 v149, v214, v206
	global_store_dwordx4 v[158:159], v[146:149], off
	v_mul_f32_e32 v150, v150, v0
	v_mul_f32_e32 v151, v151, v0
	v_mul_f32_e32 v146, v154, v0
	v_mul_f32_e32 v147, v155, v0
	v_mul_f32_e32 v148, v156, v0
	v_mul_f32_e32 v149, v157, v0
	v_mul_f32_e32 v152, v152, v0
	v_mul_f32_e32 v0, v153, v0
	v_cvt_pk_bf16_f32 v146, v146, v147
	v_cvt_pk_bf16_f32 v147, v148, v149
	v_cvt_pk_bf16_f32 v148, v150, v151
	v_cvt_pk_bf16_f32 v149, v152, v0
	global_store_dwordx4 v[158:159], v[146:149], off offset:64

.LBB0_272:
	v_or_b32_e32 v0, 16, v171
	v_add_u32_e32 v204, s29, v0
	s_mov_b64 s[44:45], -1
	s_mov_b64 s[0:1], 0
	s_cmp_lt_i32 s13, 1
	s_mov_b64 s[8:9], 0
	s_cbranch_scc1 .LBB0_276
	s_cmp_eq_u32 s13, 1
	s_mov_b64 s[8:9], -1
	s_cbranch_scc0 .LBB0_275
	s_mov_b32 s100, 0x3d372713
	s_mov_b32 s101, 0x3f4c422a
	v_mov_b32_e32 v248, 0xc038aa3b
	v_pk_mul_f32 v[238:239], v[130:131], s[100:101] op_sel_hi:[1,0]
	v_pk_mul_f32 v[238:239], v[130:131], v[238:239]
	v_pk_fma_f32 v[238:239], v[130:131], v[238:239], v[130:131]
	v_pk_mul_f32 v[238:239], v[238:239], s[100:101] op_sel:[0,1] op_sel_hi:[1,1]
	v_pk_mul_f32 v[238:239], v[238:239], v[248:249] op_sel_hi:[1,0]
	v_exp_f32_e32 v238, v238
	v_exp_f32_e32 v239, v239
	s_nop 0
	v_pk_add_f32 v[238:239], v[238:239], 1.0 op_sel_hi:[1,0]
	v_rcp_f32_e32 v144, v238
	v_rcp_f32_e32 v145, v239
	v_pk_mul_f32 v[240:241], v[132:133], s[100:101] op_sel_hi:[1,0]
	v_pk_mul_f32 v[240:241], v[132:133], v[240:241]
	v_pk_fma_f32 v[240:241], v[132:133], v[240:241], v[132:133]
	v_pk_mul_f32 v[240:241], v[240:241], s[100:101] op_sel:[0,1] op_sel_hi:[1,1]
	v_pk_mul_f32 v[240:241], v[240:241], v[248:249] op_sel_hi:[1,0]
	v_exp_f32_e32 v240, v240
	v_exp_f32_e32 v241, v241
	s_nop 0
	v_pk_add_f32 v[240:241], v[240:241], 1.0 op_sel_hi:[1,0]
	v_rcp_f32_e32 v162, v240
	v_rcp_f32_e32 v163, v241
	v_pk_mul_f32 v[242:243], v[126:127], s[100:101] op_sel_hi:[1,0]
	v_pk_mul_f32 v[242:243], v[126:127], v[242:243]
	v_pk_fma_f32 v[242:243], v[126:127], v[242:243], v[126:127]
	v_pk_mul_f32 v[242:243], v[242:243], s[100:101] op_sel:[0,1] op_sel_hi:[1,1]
	v_pk_mul_f32 v[242:243], v[242:243], v[248:249] op_sel_hi:[1,0]
	v_exp_f32_e32 v242, v242
	v_exp_f32_e32 v243, v243
	s_nop 0
	v_pk_add_f32 v[242:243], v[242:243], 1.0 op_sel_hi:[1,0]
	v_rcp_f32_e32 v164, v242
	v_rcp_f32_e32 v165, v243
	v_pk_mul_f32 v[244:245], v[128:129], s[100:101] op_sel_hi:[1,0]
	v_pk_mul_f32 v[244:245], v[128:129], v[244:245]
	v_pk_fma_f32 v[244:245], v[128:129], v[244:245], v[128:129]
	v_pk_mul_f32 v[244:245], v[244:245], s[100:101] op_sel:[0,1] op_sel_hi:[1,1]
	v_pk_mul_f32 v[244:245], v[244:245], v[248:249] op_sel_hi:[1,0]
	v_exp_f32_e32 v244, v244
	v_exp_f32_e32 v245, v245
	s_nop 0
	v_pk_add_f32 v[244:245], v[244:245], 1.0 op_sel_hi:[1,0]
	v_rcp_f32_e32 v205, v244
	v_rcp_f32_e32 v206, v245
	v_fma_f32 v140, v130, v144, 0
	v_pk_mul_f32 v[246:247], v[122:123], s[100:101] op_sel_hi:[1,0]
	v_pk_mul_f32 v[246:247], v[122:123], v[246:247]
	v_pk_fma_f32 v[246:247], v[122:123], v[246:247], v[122:123]
	v_pk_mul_f32 v[246:247], v[246:247], s[100:101] op_sel:[0,1] op_sel_hi:[1,1]
	v_pk_mul_f32 v[246:247], v[246:247], v[248:249] op_sel_hi:[1,0]
	v_exp_f32_e32 v246, v246
	v_exp_f32_e32 v247, v247
	s_nop 0
	v_pk_add_f32 v[246:247], v[246:247], 1.0 op_sel_hi:[1,0]
	v_rcp_f32_e32 v134, v246
	v_fmac_f32_e32 v140, v131, v145
	v_fmac_f32_e32 v140, v132, v162
	v_fmac_f32_e32 v140, v133, v163
	v_rcp_f32_e32 v135, v247
	v_fmac_f32_e32 v140, v126, v164
	v_fmac_f32_e32 v140, v127, v165
	v_fmac_f32_e32 v140, v128, v205
	v_fmac_f32_e32 v140, v129, v206
	v_pk_mul_f32 v[238:239], v[124:125], s[100:101] op_sel_hi:[1,0]
	v_pk_mul_f32 v[238:239], v[124:125], v[238:239]
	v_pk_fma_f32 v[238:239], v[124:125], v[238:239], v[124:125]
	v_pk_mul_f32 v[238:239], v[238:239], s[100:101] op_sel:[0,1] op_sel_hi:[1,1]
	v_pk_mul_f32 v[238:239], v[238:239], v[248:249] op_sel_hi:[1,0]
	v_exp_f32_e32 v238, v238
	v_exp_f32_e32 v239, v239
	s_nop 0
	v_pk_add_f32 v[238:239], v[238:239], 1.0 op_sel_hi:[1,0]
	v_rcp_f32_e32 v136, v238
	v_pk_mul_f32 v[138:139], v[122:123], v[134:135]
	v_rcp_f32_e32 v137, v239
	v_add_f32_e32 v0, v140, v138
	v_add_f32_e32 v0, v139, v0
	v_pk_mul_f32 v[138:139], v[124:125], v[136:137]
	v_add_f32_e32 v0, v138, v0
	v_add_f32_e32 v0, v139, v0
	v_pk_mul_f32 v[240:241], v[118:119], s[100:101] op_sel_hi:[1,0]
	v_pk_mul_f32 v[240:241], v[118:119], v[240:241]
	v_pk_fma_f32 v[240:241], v[118:119], v[240:241], v[118:119]
	v_pk_mul_f32 v[240:241], v[240:241], s[100:101] op_sel:[0,1] op_sel_hi:[1,1]
	v_pk_mul_f32 v[240:241], v[240:241], v[248:249] op_sel_hi:[1,0]
	v_exp_f32_e32 v240, v240
	v_exp_f32_e32 v241, v241
	s_nop 0
	v_pk_add_f32 v[240:241], v[240:241], 1.0 op_sel_hi:[1,0]
	v_rcp_f32_e32 v138, v240
	v_rcp_f32_e32 v139, v241
	v_pk_mul_f32 v[242:243], v[120:121], s[100:101] op_sel_hi:[1,0]
	v_pk_mul_f32 v[242:243], v[120:121], v[242:243]
	v_pk_fma_f32 v[242:243], v[120:121], v[242:243], v[120:121]
	v_pk_mul_f32 v[242:243], v[242:243], s[100:101] op_sel:[0,1] op_sel_hi:[1,1]
	v_pk_mul_f32 v[242:243], v[242:243], v[248:249] op_sel_hi:[1,0]
	v_exp_f32_e32 v242, v242
	v_exp_f32_e32 v243, v243
	s_nop 0
	v_pk_add_f32 v[242:243], v[242:243], 1.0 op_sel_hi:[1,0]
	v_rcp_f32_e32 v140, v242
	v_rcp_f32_e32 v141, v243
	v_pk_mul_f32 v[142:143], v[118:119], v[138:139]
	s_mov_b64 s[8:9], 0
	v_add_f32_e32 v0, v142, v0
	v_add_f32_e32 v0, v143, v0
	v_pk_mul_f32 v[142:143], v[120:121], v[140:141]
	s_nop 0
	v_add_f32_e32 v0, v142, v0
	v_add_f32_e32 v0, v143, v0
	v_and_b32_e32 v143, 64, v224
	v_xor_b32_e32 v142, 16, v224
	v_add_u32_e32 v143, 64, v143
	v_cmp_lt_i32_e32 vcc, v142, v143
	s_nop 1
	v_cndmask_b32_e32 v142, v224, v142, vcc
	v_lshlrev_b32_e32 v207, 2, v142
	ds_bpermute_b32 v142, v207, v0
	s_waitcnt lgkmcnt(0)
	v_add_f32_e32 v0, v0, v142
	v_xor_b32_e32 v142, 32, v224
	v_cmp_lt_i32_e32 vcc, v142, v143
	s_nop 1
	v_cndmask_b32_e32 v142, v224, v142, vcc
	v_lshlrev_b32_e32 v215, 2, v142
	ds_bpermute_b32 v142, v215, v0
	s_waitcnt lgkmcnt(0)
	v_add_f32_e32 v0, v0, v142
	v_mul_f32_e32 v0, 0x3c800000, v0
	v_fma_f32 v217, v131, v145, -v0
	v_fma_f32 v216, v130, v144, -v0
	v_mul_f32_e32 v144, v217, v217
	v_fmac_f32_e32 v144, v216, v216
	v_fma_f32 v162, v132, v162, -v0
	v_fmac_f32_e32 v144, v162, v162
	v_fma_f32 v163, v133, v163, -v0
	v_fmac_f32_e32 v144, v163, v163
	v_fma_f32 v164, v126, v164, -v0
	v_fmac_f32_e32 v144, v164, v164
	v_fma_f32 v165, v127, v165, -v0
	v_fmac_f32_e32 v144, v165, v165
	v_fma_f32 v218, v128, v205, -v0
	v_fmac_f32_e32 v144, v218, v218
	v_fma_f32 v206, v129, v206, -v0
	v_pk_fma_f32 v[142:143], v[122:123], v[134:135], v[0:1] op_sel_hi:[1,1,0] neg_lo:[0,0,1] neg_hi:[0,0,1]
	v_fmac_f32_e32 v144, v206, v206
	v_pk_mul_f32 v[134:135], v[142:143], v[142:143]
	v_pk_fma_f32 v[138:139], v[118:119], v[138:139], v[0:1] op_sel_hi:[1,1,0] neg_lo:[0,0,1] neg_hi:[0,0,1]
	v_add_f32_e32 v134, v134, v144
	v_pk_fma_f32 v[144:145], v[124:125], v[136:137], v[0:1] op_sel_hi:[1,1,0] neg_lo:[0,0,1] neg_hi:[0,0,1]
	v_add_f32_e32 v205, v135, v134
	v_pk_mul_f32 v[134:135], v[144:145], v[144:145]
	v_pk_fma_f32 v[140:141], v[120:121], v[140:141], v[0:1] op_sel_hi:[1,1,0] neg_lo:[0,0,1] neg_hi:[0,0,1]
	v_add_f32_e32 v134, v134, v205
	v_add_f32_e32 v136, v135, v134
	v_pk_mul_f32 v[134:135], v[138:139], v[138:139]
	v_ashrrev_i32_e32 v205, 31, v204
	v_add_f32_e32 v134, v134, v136
	v_add_f32_e32 v136, v135, v134
	v_pk_mul_f32 v[134:135], v[140:141], v[140:141]
	s_nop 0
	v_add_f32_e32 v0, v134, v136
	v_add_f32_e32 v0, v135, v0
	ds_bpermute_b32 v134, v207, v0
	s_waitcnt lgkmcnt(0)
	v_add_f32_e32 v0, v0, v134
	ds_bpermute_b32 v134, v215, v0
	s_waitcnt lgkmcnt(0)
	v_add_f32_e32 v0, v0, v134
	v_fmamk_f32 v0, v0, 0x3c800000, v222
	v_mul_f32_e32 v134, 0x4b800000, v0
	v_cmp_gt_f32_e32 vcc, s14, v0
	s_nop 1
	v_cndmask_b32_e32 v0, v0, v134, vcc
	v_rsq_f32_e32 v0, v0
	s_nop 0
	v_mul_f32_e32 v134, 0x45800000, v0
	v_cndmask_b32_e32 v0, v0, v134, vcc
	v_lshlrev_b64 v[134:135], 9, v[204:205]
	v_mul_f32_e32 v136, v216, v0
	v_mul_f32_e32 v137, v217, v0
	v_mul_f32_e32 v205, v162, v0
	v_mul_f32_e32 v207, v163, v0
	v_mul_f32_e32 v164, v164, v0
	v_mul_f32_e32 v165, v165, v0
	v_mul_f32_e32 v215, v218, v0
	v_mul_f32_e32 v206, v206, v0
	v_lshl_add_u64 v[162:163], v[196:197], 0, v[134:135]
	v_cvt_pk_bf16_f32 v134, v136, v137
	v_cvt_pk_bf16_f32 v135, v205, v207
	v_cvt_pk_bf16_f32 v136, v164, v165
	v_cvt_pk_bf16_f32 v137, v215, v206
	global_store_dwordx4 v[162:163], v[134:137], off
	v_mul_f32_e32 v138, v138, v0
	v_mul_f32_e32 v139, v139, v0
	v_mul_f32_e32 v134, v142, v0
	v_mul_f32_e32 v135, v143, v0
	v_mul_f32_e32 v136, v144, v0
	v_mul_f32_e32 v137, v145, v0
	v_mul_f32_e32 v140, v140, v0
	v_mul_f32_e32 v0, v141, v0
	v_cvt_pk_bf16_f32 v134, v134, v135
	v_cvt_pk_bf16_f32 v135, v136, v137
	v_cvt_pk_bf16_f32 v136, v138, v139
	v_cvt_pk_bf16_f32 v137, v140, v0
	global_store_dwordx4 v[162:163], v[134:137], off offset:64

.LBB0_317:
	v_add_u32_e32 v146, s29, v175
	s_mov_b64 s[44:45], -1
	s_mov_b64 s[0:1], 0
	s_cmp_lt_i32 s13, 1
	s_mov_b64 s[8:9], 0
	s_cbranch_scc1 .LBB0_321
	s_cmp_eq_u32 s13, 1
	s_mov_b64 s[8:9], -1
	s_cbranch_scc0 .LBB0_320
	s_mov_b32 s100, 0x3d372713
	s_mov_b32 s101, 0x3f4c422a
	v_mov_b32_e32 v248, 0xc038aa3b
	v_pk_mul_f32 v[238:239], v[114:115], s[100:101] op_sel_hi:[1,0]
	v_pk_mul_f32 v[238:239], v[114:115], v[238:239]
	v_pk_fma_f32 v[238:239], v[114:115], v[238:239], v[114:115]
	v_pk_mul_f32 v[238:239], v[238:239], s[100:101] op_sel:[0,1] op_sel_hi:[1,1]
	v_pk_mul_f32 v[238:239], v[238:239], v[248:249] op_sel_hi:[1,0]
	v_exp_f32_e32 v238, v238
	v_exp_f32_e32 v239, v239
	s_nop 0
	v_pk_add_f32 v[238:239], v[238:239], 1.0 op_sel_hi:[1,0]
	v_rcp_f32_e32 v128, v238
	v_rcp_f32_e32 v129, v239
	v_pk_mul_f32 v[240:241], v[116:117], s[100:101] op_sel_hi:[1,0]
	v_pk_mul_f32 v[240:241], v[116:117], v[240:241]
	v_pk_fma_f32 v[240:241], v[116:117], v[240:241], v[116:117]
	v_pk_mul_f32 v[240:241], v[240:241], s[100:101] op_sel:[0,1] op_sel_hi:[1,1]
	v_pk_mul_f32 v[240:241], v[240:241], v[248:249] op_sel_hi:[1,0]
	v_exp_f32_e32 v240, v240
	v_exp_f32_e32 v241, v241
	s_nop 0
	v_pk_add_f32 v[240:241], v[240:241], 1.0 op_sel_hi:[1,0]
	v_rcp_f32_e32 v130, v240
	v_rcp_f32_e32 v131, v241
	v_pk_mul_f32 v[242:243], v[110:111], s[100:101] op_sel_hi:[1,0]
	v_pk_mul_f32 v[242:243], v[110:111], v[242:243]
	v_pk_fma_f32 v[242:243], v[110:111], v[242:243], v[110:111]
	v_pk_mul_f32 v[242:243], v[242:243], s[100:101] op_sel:[0,1] op_sel_hi:[1,1]
	v_pk_mul_f32 v[242:243], v[242:243], v[248:249] op_sel_hi:[1,0]
	v_exp_f32_e32 v242, v242
	v_exp_f32_e32 v243, v243
	s_nop 0
	v_pk_add_f32 v[242:243], v[242:243], 1.0 op_sel_hi:[1,0]
	v_rcp_f32_e32 v132, v242
	v_rcp_f32_e32 v133, v243
	v_pk_mul_f32 v[244:245], v[112:113], s[100:101] op_sel_hi:[1,0]
	v_pk_mul_f32 v[244:245], v[112:113], v[244:245]
	v_pk_fma_f32 v[244:245], v[112:113], v[244:245], v[112:113]
	v_pk_mul_f32 v[244:245], v[244:245], s[100:101] op_sel:[0,1] op_sel_hi:[1,1]
	v_pk_mul_f32 v[244:245], v[244:245], v[248:249] op_sel_hi:[1,0]
	v_exp_f32_e32 v244, v244
	v_exp_f32_e32 v245, v245
	s_nop 0
	v_pk_add_f32 v[244:245], v[244:245], 1.0 op_sel_hi:[1,0]
	v_rcp_f32_e32 v147, v244
	v_rcp_f32_e32 v148, v245
	v_fma_f32 v124, v114, v128, 0
	v_pk_mul_f32 v[246:247], v[106:107], s[100:101] op_sel_hi:[1,0]
	v_pk_mul_f32 v[246:247], v[106:107], v[246:247]
	v_pk_fma_f32 v[246:247], v[106:107], v[246:247], v[106:107]
	v_pk_mul_f32 v[246:247], v[246:247], s[100:101] op_sel:[0,1] op_sel_hi:[1,1]
	v_pk_mul_f32 v[246:247], v[246:247], v[248:249] op_sel_hi:[1,0]
	v_exp_f32_e32 v246, v246
	v_exp_f32_e32 v247, v247
	s_nop 0
	v_pk_add_f32 v[246:247], v[246:247], 1.0 op_sel_hi:[1,0]
	v_rcp_f32_e32 v118, v246
	v_fmac_f32_e32 v124, v115, v129
	v_fmac_f32_e32 v124, v116, v130
	v_fmac_f32_e32 v124, v117, v131
	v_rcp_f32_e32 v119, v247
	v_fmac_f32_e32 v124, v110, v132
	v_fmac_f32_e32 v124, v111, v133
	v_fmac_f32_e32 v124, v112, v147
	v_fmac_f32_e32 v124, v113, v148
	v_pk_mul_f32 v[238:239], v[108:109], s[100:101] op_sel_hi:[1,0]
	v_pk_mul_f32 v[238:239], v[108:109], v[238:239]
	v_pk_fma_f32 v[238:239], v[108:109], v[238:239], v[108:109]
	v_pk_mul_f32 v[238:239], v[238:239], s[100:101] op_sel:[0,1] op_sel_hi:[1,1]
	v_pk_mul_f32 v[238:239], v[238:239], v[248:249] op_sel_hi:[1,0]
	v_exp_f32_e32 v238, v238
	v_exp_f32_e32 v239, v239
	s_nop 0
	v_pk_add_f32 v[238:239], v[238:239], 1.0 op_sel_hi:[1,0]
	v_rcp_f32_e32 v120, v238
	v_pk_mul_f32 v[122:123], v[106:107], v[118:119]
	v_rcp_f32_e32 v121, v239
	v_add_f32_e32 v0, v124, v122
	v_add_f32_e32 v0, v123, v0
	v_pk_mul_f32 v[122:123], v[108:109], v[120:121]
	v_add_f32_e32 v0, v122, v0
	v_add_f32_e32 v0, v123, v0
	v_pk_mul_f32 v[240:241], v[102:103], s[100:101] op_sel_hi:[1,0]
	v_pk_mul_f32 v[240:241], v[102:103], v[240:241]
	v_pk_fma_f32 v[240:241], v[102:103], v[240:241], v[102:103]
	v_pk_mul_f32 v[240:241], v[240:241], s[100:101] op_sel:[0,1] op_sel_hi:[1,1]
	v_pk_mul_f32 v[240:241], v[240:241], v[248:249] op_sel_hi:[1,0]
	v_exp_f32_e32 v240, v240
	v_exp_f32_e32 v241, v241
	s_nop 0
	v_pk_add_f32 v[240:241], v[240:241], 1.0 op_sel_hi:[1,0]
	v_rcp_f32_e32 v122, v240
	v_rcp_f32_e32 v123, v241
	v_pk_mul_f32 v[242:243], v[104:105], s[100:101] op_sel_hi:[1,0]
	v_pk_mul_f32 v[242:243], v[104:105], v[242:243]
	v_pk_fma_f32 v[242:243], v[104:105], v[242:243], v[104:105]
	v_pk_mul_f32 v[242:243], v[242:243], s[100:101] op_sel:[0,1] op_sel_hi:[1,1]
	v_pk_mul_f32 v[242:243], v[242:243], v[248:249] op_sel_hi:[1,0]
	v_exp_f32_e32 v242, v242
	v_exp_f32_e32 v243, v243
	s_nop 0
	v_pk_add_f32 v[242:243], v[242:243], 1.0 op_sel_hi:[1,0]
	v_rcp_f32_e32 v124, v242
	v_rcp_f32_e32 v125, v243
	v_pk_mul_f32 v[126:127], v[102:103], v[122:123]
	s_mov_b64 s[8:9], 0
	v_add_f32_e32 v0, v126, v0
	v_add_f32_e32 v0, v127, v0
	v_pk_mul_f32 v[126:127], v[104:105], v[124:125]
	s_nop 0
	v_add_f32_e32 v0, v126, v0
	v_add_f32_e32 v0, v127, v0
	v_and_b32_e32 v127, 64, v224
	v_xor_b32_e32 v126, 16, v224
	v_add_u32_e32 v127, 64, v127
	v_cmp_lt_i32_e32 vcc, v126, v127
	s_nop 1
	v_cndmask_b32_e32 v126, v224, v126, vcc
	v_lshlrev_b32_e32 v149, 2, v126
	ds_bpermute_b32 v126, v149, v0
	s_waitcnt lgkmcnt(0)
	v_add_f32_e32 v0, v0, v126
	v_xor_b32_e32 v126, 32, v224
	v_cmp_lt_i32_e32 vcc, v126, v127
	s_nop 1
	v_cndmask_b32_e32 v126, v224, v126, vcc
	v_lshlrev_b32_e32 v150, 2, v126
	ds_bpermute_b32 v126, v150, v0
	s_waitcnt lgkmcnt(0)
	v_add_f32_e32 v0, v0, v126
	v_mul_f32_e32 v0, 0x3c800000, v0
	v_fma_f32 v152, v115, v129, -v0
	v_fma_f32 v151, v114, v128, -v0
	v_mul_f32_e32 v128, v152, v152
	v_fmac_f32_e32 v128, v151, v151
	v_fma_f32 v130, v116, v130, -v0
	v_fmac_f32_e32 v128, v130, v130
	v_fma_f32 v131, v117, v131, -v0
	v_fmac_f32_e32 v128, v131, v131
	v_fma_f32 v132, v110, v132, -v0
	v_fmac_f32_e32 v128, v132, v132
	v_fma_f32 v133, v111, v133, -v0
	v_fmac_f32_e32 v128, v133, v133
	v_fma_f32 v153, v112, v147, -v0
	v_fmac_f32_e32 v128, v153, v153
	v_fma_f32 v148, v113, v148, -v0
	v_pk_fma_f32 v[126:127], v[106:107], v[118:119], v[0:1] op_sel_hi:[1,1,0] neg_lo:[0,0,1] neg_hi:[0,0,1]
	v_fmac_f32_e32 v128, v148, v148
	v_pk_mul_f32 v[118:119], v[126:127], v[126:127]
	v_pk_fma_f32 v[122:123], v[102:103], v[122:123], v[0:1] op_sel_hi:[1,1,0] neg_lo:[0,0,1] neg_hi:[0,0,1]
	v_add_f32_e32 v118, v118, v128
	v_pk_fma_f32 v[128:129], v[108:109], v[120:121], v[0:1] op_sel_hi:[1,1,0] neg_lo:[0,0,1] neg_hi:[0,0,1]
	v_add_f32_e32 v147, v119, v118
	v_pk_mul_f32 v[118:119], v[128:129], v[128:129]
	v_pk_fma_f32 v[124:125], v[104:105], v[124:125], v[0:1] op_sel_hi:[1,1,0] neg_lo:[0,0,1] neg_hi:[0,0,1]
	v_add_f32_e32 v118, v118, v147
	v_add_f32_e32 v120, v119, v118
	v_pk_mul_f32 v[118:119], v[122:123], v[122:123]
	v_ashrrev_i32_e32 v147, 31, v146
	v_add_f32_e32 v118, v118, v120
	v_add_f32_e32 v120, v119, v118
	v_pk_mul_f32 v[118:119], v[124:125], v[124:125]
	s_nop 0
	v_add_f32_e32 v0, v118, v120
	v_add_f32_e32 v0, v119, v0
	ds_bpermute_b32 v118, v149, v0
	s_waitcnt lgkmcnt(0)
	v_add_f32_e32 v0, v0, v118
	ds_bpermute_b32 v118, v150, v0
	s_waitcnt lgkmcnt(0)
	v_add_f32_e32 v0, v0, v118
	v_fmamk_f32 v0, v0, 0x3c800000, v222
	v_mul_f32_e32 v118, 0x4b800000, v0
	v_cmp_gt_f32_e32 vcc, s14, v0
	s_nop 1
	v_cndmask_b32_e32 v0, v0, v118, vcc
	v_rsq_f32_e32 v0, v0
	s_nop 0
	v_mul_f32_e32 v118, 0x45800000, v0
	v_cndmask_b32_e32 v0, v0, v118, vcc
	v_lshlrev_b64 v[118:119], 9, v[146:147]
	v_mul_f32_e32 v120, v151, v0
	v_mul_f32_e32 v121, v152, v0
	v_mul_f32_e32 v147, v130, v0
	v_mul_f32_e32 v149, v131, v0
	v_mul_f32_e32 v132, v132, v0
	v_mul_f32_e32 v133, v133, v0
	v_mul_f32_e32 v150, v153, v0
	v_mul_f32_e32 v148, v148, v0
	v_lshl_add_u64 v[130:131], v[196:197], 0, v[118:119]
	v_cvt_pk_bf16_f32 v118, v120, v121
	v_cvt_pk_bf16_f32 v119, v147, v149
	v_cvt_pk_bf16_f32 v120, v132, v133
	v_cvt_pk_bf16_f32 v121, v150, v148
	global_store_dwordx4 v[130:131], v[118:121], off
	v_mul_f32_e32 v122, v122, v0
	v_mul_f32_e32 v123, v123, v0
	v_mul_f32_e32 v118, v126, v0
	v_mul_f32_e32 v119, v127, v0
	v_mul_f32_e32 v120, v128, v0
	v_mul_f32_e32 v121, v129, v0
	v_mul_f32_e32 v124, v124, v0
	v_mul_f32_e32 v0, v125, v0
	v_cvt_pk_bf16_f32 v118, v118, v119
	v_cvt_pk_bf16_f32 v119, v120, v121
	v_cvt_pk_bf16_f32 v120, v122, v123
	v_cvt_pk_bf16_f32 v121, v124, v0
	global_store_dwordx4 v[130:131], v[118:121], off offset:64

.LBB0_362:
	v_add_u32_e32 v134, s29, v177
	s_mov_b64 s[44:45], -1
	s_mov_b64 s[0:1], 0
	s_cmp_lt_i32 s13, 1
	s_mov_b64 s[8:9], 0
	s_cbranch_scc1 .LBB0_366
	s_cmp_eq_u32 s13, 1
	s_mov_b64 s[8:9], -1
	s_cbranch_scc0 .LBB0_365
	s_mov_b32 s100, 0x3d372713
	s_mov_b32 s101, 0x3f4c422a
	v_mov_b32_e32 v248, 0xc038aa3b
	v_pk_mul_f32 v[238:239], v[98:99], s[100:101] op_sel_hi:[1,0]
	v_pk_mul_f32 v[238:239], v[98:99], v[238:239]
	v_pk_fma_f32 v[238:239], v[98:99], v[238:239], v[98:99]
	v_pk_mul_f32 v[238:239], v[238:239], s[100:101] op_sel:[0,1] op_sel_hi:[1,1]
	v_pk_mul_f32 v[238:239], v[238:239], v[248:249] op_sel_hi:[1,0]
	v_exp_f32_e32 v238, v238
	v_exp_f32_e32 v239, v239
	s_nop 0
	v_pk_add_f32 v[238:239], v[238:239], 1.0 op_sel_hi:[1,0]
	v_rcp_f32_e32 v112, v238
	v_rcp_f32_e32 v113, v239
	v_pk_mul_f32 v[240:241], v[100:101], s[100:101] op_sel_hi:[1,0]
	v_pk_mul_f32 v[240:241], v[100:101], v[240:241]
	v_pk_fma_f32 v[240:241], v[100:101], v[240:241], v[100:101]
	v_pk_mul_f32 v[240:241], v[240:241], s[100:101] op_sel:[0,1] op_sel_hi:[1,1]
	v_pk_mul_f32 v[240:241], v[240:241], v[248:249] op_sel_hi:[1,0]
	v_exp_f32_e32 v240, v240
	v_exp_f32_e32 v241, v241
	s_nop 0
	v_pk_add_f32 v[240:241], v[240:241], 1.0 op_sel_hi:[1,0]
	v_rcp_f32_e32 v114, v240
	v_rcp_f32_e32 v115, v241
	v_pk_mul_f32 v[242:243], v[94:95], s[100:101] op_sel_hi:[1,0]
	v_pk_mul_f32 v[242:243], v[94:95], v[242:243]
	v_pk_fma_f32 v[242:243], v[94:95], v[242:243], v[94:95]
	v_pk_mul_f32 v[242:243], v[242:243], s[100:101] op_sel:[0,1] op_sel_hi:[1,1]
	v_pk_mul_f32 v[242:243], v[242:243], v[248:249] op_sel_hi:[1,0]
	v_exp_f32_e32 v242, v242
	v_exp_f32_e32 v243, v243
	s_nop 0
	v_pk_add_f32 v[242:243], v[242:243], 1.0 op_sel_hi:[1,0]
	v_rcp_f32_e32 v116, v242
	v_rcp_f32_e32 v117, v243
	v_pk_mul_f32 v[244:245], v[96:97], s[100:101] op_sel_hi:[1,0]
	v_pk_mul_f32 v[244:245], v[96:97], v[244:245]
	v_pk_fma_f32 v[244:245], v[96:97], v[244:245], v[96:97]
	v_pk_mul_f32 v[244:245], v[244:245], s[100:101] op_sel:[0,1] op_sel_hi:[1,1]
	v_pk_mul_f32 v[244:245], v[244:245], v[248:249] op_sel_hi:[1,0]
	v_exp_f32_e32 v244, v244
	v_exp_f32_e32 v245, v245
	s_nop 0
	v_pk_add_f32 v[244:245], v[244:245], 1.0 op_sel_hi:[1,0]
	v_rcp_f32_e32 v135, v244
	v_rcp_f32_e32 v136, v245
	v_fma_f32 v108, v98, v112, 0
	v_pk_mul_f32 v[246:247], v[90:91], s[100:101] op_sel_hi:[1,0]
	v_pk_mul_f32 v[246:247], v[90:91], v[246:247]
	v_pk_fma_f32 v[246:247], v[90:91], v[246:247], v[90:91]
	v_pk_mul_f32 v[246:247], v[246:247], s[100:101] op_sel:[0,1] op_sel_hi:[1,1]
	v_pk_mul_f32 v[246:247], v[246:247], v[248:249] op_sel_hi:[1,0]
	v_exp_f32_e32 v246, v246
	v_exp_f32_e32 v247, v247
	s_nop 0
	v_pk_add_f32 v[246:247], v[246:247], 1.0 op_sel_hi:[1,0]
	v_rcp_f32_e32 v102, v246
	v_fmac_f32_e32 v108, v99, v113
	v_fmac_f32_e32 v108, v100, v114
	v_fmac_f32_e32 v108, v101, v115
	v_rcp_f32_e32 v103, v247
	v_fmac_f32_e32 v108, v94, v116
	v_fmac_f32_e32 v108, v95, v117
	v_fmac_f32_e32 v108, v96, v135
	v_fmac_f32_e32 v108, v97, v136
	v_pk_mul_f32 v[238:239], v[92:93], s[100:101] op_sel_hi:[1,0]
	v_pk_mul_f32 v[238:239], v[92:93], v[238:239]
	v_pk_fma_f32 v[238:239], v[92:93], v[238:239], v[92:93]
	v_pk_mul_f32 v[238:239], v[238:239], s[100:101] op_sel:[0,1] op_sel_hi:[1,1]
	v_pk_mul_f32 v[238:239], v[238:239], v[248:249] op_sel_hi:[1,0]
	v_exp_f32_e32 v238, v238
	v_exp_f32_e32 v239, v239
	s_nop 0
	v_pk_add_f32 v[238:239], v[238:239], 1.0 op_sel_hi:[1,0]
	v_rcp_f32_e32 v104, v238
	v_pk_mul_f32 v[106:107], v[90:91], v[102:103]
	v_rcp_f32_e32 v105, v239
	v_add_f32_e32 v0, v108, v106
	v_add_f32_e32 v0, v107, v0
	v_pk_mul_f32 v[106:107], v[92:93], v[104:105]
	v_add_f32_e32 v0, v106, v0
	v_add_f32_e32 v0, v107, v0
	v_pk_mul_f32 v[240:241], v[86:87], s[100:101] op_sel_hi:[1,0]
	v_pk_mul_f32 v[240:241], v[86:87], v[240:241]
	v_pk_fma_f32 v[240:241], v[86:87], v[240:241], v[86:87]
	v_pk_mul_f32 v[240:241], v[240:241], s[100:101] op_sel:[0,1] op_sel_hi:[1,1]
	v_pk_mul_f32 v[240:241], v[240:241], v[248:249] op_sel_hi:[1,0]
	v_exp_f32_e32 v240, v240
	v_exp_f32_e32 v241, v241
	s_nop 0
	v_pk_add_f32 v[240:241], v[240:241], 1.0 op_sel_hi:[1,0]
	v_rcp_f32_e32 v106, v240
	v_rcp_f32_e32 v107, v241
	v_pk_mul_f32 v[242:243], v[88:89], s[100:101] op_sel_hi:[1,0]
	v_pk_mul_f32 v[242:243], v[88:89], v[242:243]
	v_pk_fma_f32 v[242:243], v[88:89], v[242:243], v[88:89]
	v_pk_mul_f32 v[242:243], v[242:243], s[100:101] op_sel:[0,1] op_sel_hi:[1,1]
	v_pk_mul_f32 v[242:243], v[242:243], v[248:249] op_sel_hi:[1,0]
	v_exp_f32_e32 v242, v242
	v_exp_f32_e32 v243, v243
	s_nop 0
	v_pk_add_f32 v[242:243], v[242:243], 1.0 op_sel_hi:[1,0]
	v_rcp_f32_e32 v108, v242
	v_rcp_f32_e32 v109, v243
	v_pk_mul_f32 v[110:111], v[86:87], v[106:107]
	s_mov_b64 s[8:9], 0
	v_add_f32_e32 v0, v110, v0
	v_add_f32_e32 v0, v111, v0
	v_pk_mul_f32 v[110:111], v[88:89], v[108:109]
	s_nop 0
	v_add_f32_e32 v0, v110, v0
	v_add_f32_e32 v0, v111, v0
	v_and_b32_e32 v111, 64, v224
	v_xor_b32_e32 v110, 16, v224
	v_add_u32_e32 v111, 64, v111
	v_cmp_lt_i32_e32 vcc, v110, v111
	s_nop 1
	v_cndmask_b32_e32 v110, v224, v110, vcc
	v_lshlrev_b32_e32 v137, 2, v110
	ds_bpermute_b32 v110, v137, v0
	s_waitcnt lgkmcnt(0)
	v_add_f32_e32 v0, v0, v110
	v_xor_b32_e32 v110, 32, v224
	v_cmp_lt_i32_e32 vcc, v110, v111
	s_nop 1
	v_cndmask_b32_e32 v110, v224, v110, vcc
	v_lshlrev_b32_e32 v138, 2, v110
	ds_bpermute_b32 v110, v138, v0
	s_waitcnt lgkmcnt(0)
	v_add_f32_e32 v0, v0, v110
	v_mul_f32_e32 v0, 0x3c800000, v0
	v_fma_f32 v140, v99, v113, -v0
	v_fma_f32 v139, v98, v112, -v0
	v_mul_f32_e32 v112, v140, v140
	v_fmac_f32_e32 v112, v139, v139
	v_fma_f32 v114, v100, v114, -v0
	v_fmac_f32_e32 v112, v114, v114
	v_fma_f32 v115, v101, v115, -v0
	v_fmac_f32_e32 v112, v115, v115
	v_fma_f32 v116, v94, v116, -v0
	v_fmac_f32_e32 v112, v116, v116
	v_fma_f32 v117, v95, v117, -v0
	v_fmac_f32_e32 v112, v117, v117
	v_fma_f32 v141, v96, v135, -v0
	v_fmac_f32_e32 v112, v141, v141
	v_fma_f32 v136, v97, v136, -v0
	v_pk_fma_f32 v[110:111], v[90:91], v[102:103], v[0:1] op_sel_hi:[1,1,0] neg_lo:[0,0,1] neg_hi:[0,0,1]
	v_fmac_f32_e32 v112, v136, v136
	v_pk_mul_f32 v[102:103], v[110:111], v[110:111]
	v_pk_fma_f32 v[106:107], v[86:87], v[106:107], v[0:1] op_sel_hi:[1,1,0] neg_lo:[0,0,1] neg_hi:[0,0,1]
	v_add_f32_e32 v102, v102, v112
	v_pk_fma_f32 v[112:113], v[92:93], v[104:105], v[0:1] op_sel_hi:[1,1,0] neg_lo:[0,0,1] neg_hi:[0,0,1]
	v_add_f32_e32 v135, v103, v102
	v_pk_mul_f32 v[102:103], v[112:113], v[112:113]
	v_pk_fma_f32 v[108:109], v[88:89], v[108:109], v[0:1] op_sel_hi:[1,1,0] neg_lo:[0,0,1] neg_hi:[0,0,1]
	v_add_f32_e32 v102, v102, v135
	v_add_f32_e32 v104, v103, v102
	v_pk_mul_f32 v[102:103], v[106:107], v[106:107]
	v_ashrrev_i32_e32 v135, 31, v134
	v_add_f32_e32 v102, v102, v104
	v_add_f32_e32 v104, v103, v102
	v_pk_mul_f32 v[102:103], v[108:109], v[108:109]
	s_nop 0
	v_add_f32_e32 v0, v102, v104
	v_add_f32_e32 v0, v103, v0
	ds_bpermute_b32 v102, v137, v0
	s_waitcnt lgkmcnt(0)
	v_add_f32_e32 v0, v0, v102
	ds_bpermute_b32 v102, v138, v0
	s_waitcnt lgkmcnt(0)
	v_add_f32_e32 v0, v0, v102
	v_fmamk_f32 v0, v0, 0x3c800000, v222
	v_mul_f32_e32 v102, 0x4b800000, v0
	v_cmp_gt_f32_e32 vcc, s14, v0
	s_nop 1
	v_cndmask_b32_e32 v0, v0, v102, vcc
	v_rsq_f32_e32 v0, v0
	s_nop 0
	v_mul_f32_e32 v102, 0x45800000, v0
	v_cndmask_b32_e32 v0, v0, v102, vcc
	v_lshlrev_b64 v[102:103], 9, v[134:135]
	v_mul_f32_e32 v104, v139, v0
	v_mul_f32_e32 v105, v140, v0
	v_mul_f32_e32 v135, v114, v0
	v_mul_f32_e32 v137, v115, v0
	v_mul_f32_e32 v116, v116, v0
	v_mul_f32_e32 v117, v117, v0
	v_mul_f32_e32 v138, v141, v0
	v_mul_f32_e32 v136, v136, v0
	v_lshl_add_u64 v[114:115], v[196:197], 0, v[102:103]
	v_cvt_pk_bf16_f32 v102, v104, v105
	v_cvt_pk_bf16_f32 v103, v135, v137
	v_cvt_pk_bf16_f32 v104, v116, v117
	v_cvt_pk_bf16_f32 v105, v138, v136
	global_store_dwordx4 v[114:115], v[102:105], off
	v_mul_f32_e32 v106, v106, v0
	v_mul_f32_e32 v107, v107, v0
	v_mul_f32_e32 v102, v110, v0
	v_mul_f32_e32 v103, v111, v0
	v_mul_f32_e32 v104, v112, v0
	v_mul_f32_e32 v105, v113, v0
	v_mul_f32_e32 v108, v108, v0
	v_mul_f32_e32 v0, v109, v0
	v_cvt_pk_bf16_f32 v102, v102, v103
	v_cvt_pk_bf16_f32 v103, v104, v105
	v_cvt_pk_bf16_f32 v104, v106, v107
	v_cvt_pk_bf16_f32 v105, v108, v0
	global_store_dwordx4 v[114:115], v[102:105], off offset:64

.LBB0_407:
	v_add_u32_e32 v118, s29, v179
	s_mov_b64 s[44:45], -1
	s_mov_b64 s[0:1], 0
	s_cmp_lt_i32 s13, 1
	s_mov_b64 s[8:9], 0
	s_cbranch_scc1 .LBB0_411
	s_cmp_eq_u32 s13, 1
	s_mov_b64 s[8:9], -1
	s_cbranch_scc0 .LBB0_410
	s_mov_b32 s100, 0x3d372713
	s_mov_b32 s101, 0x3f4c422a
	v_mov_b32_e32 v248, 0xc038aa3b
	v_pk_mul_f32 v[238:239], v[82:83], s[100:101] op_sel_hi:[1,0]
	v_pk_mul_f32 v[238:239], v[82:83], v[238:239]
	v_pk_fma_f32 v[238:239], v[82:83], v[238:239], v[82:83]
	v_pk_mul_f32 v[238:239], v[238:239], s[100:101] op_sel:[0,1] op_sel_hi:[1,1]
	v_pk_mul_f32 v[238:239], v[238:239], v[248:249] op_sel_hi:[1,0]
	v_exp_f32_e32 v238, v238
	v_exp_f32_e32 v239, v239
	s_nop 0
	v_pk_add_f32 v[238:239], v[238:239], 1.0 op_sel_hi:[1,0]
	v_rcp_f32_e32 v96, v238
	v_rcp_f32_e32 v97, v239
	v_pk_mul_f32 v[240:241], v[84:85], s[100:101] op_sel_hi:[1,0]
	v_pk_mul_f32 v[240:241], v[84:85], v[240:241]
	v_pk_fma_f32 v[240:241], v[84:85], v[240:241], v[84:85]
	v_pk_mul_f32 v[240:241], v[240:241], s[100:101] op_sel:[0,1] op_sel_hi:[1,1]
	v_pk_mul_f32 v[240:241], v[240:241], v[248:249] op_sel_hi:[1,0]
	v_exp_f32_e32 v240, v240
	v_exp_f32_e32 v241, v241
	s_nop 0
	v_pk_add_f32 v[240:241], v[240:241], 1.0 op_sel_hi:[1,0]
	v_rcp_f32_e32 v98, v240
	v_rcp_f32_e32 v99, v241
	v_pk_mul_f32 v[242:243], v[78:79], s[100:101] op_sel_hi:[1,0]
	v_pk_mul_f32 v[242:243], v[78:79], v[242:243]
	v_pk_fma_f32 v[242:243], v[78:79], v[242:243], v[78:79]
	v_pk_mul_f32 v[242:243], v[242:243], s[100:101] op_sel:[0,1] op_sel_hi:[1,1]
	v_pk_mul_f32 v[242:243], v[242:243], v[248:249] op_sel_hi:[1,0]
	v_exp_f32_e32 v242, v242
	v_exp_f32_e32 v243, v243
	s_nop 0
	v_pk_add_f32 v[242:243], v[242:243], 1.0 op_sel_hi:[1,0]
	v_rcp_f32_e32 v100, v242
	v_rcp_f32_e32 v101, v243
	v_pk_mul_f32 v[244:245], v[80:81], s[100:101] op_sel_hi:[1,0]
	v_pk_mul_f32 v[244:245], v[80:81], v[244:245]
	v_pk_fma_f32 v[244:245], v[80:81], v[244:245], v[80:81]
	v_pk_mul_f32 v[244:245], v[244:245], s[100:101] op_sel:[0,1] op_sel_hi:[1,1]
	v_pk_mul_f32 v[244:245], v[244:245], v[248:249] op_sel_hi:[1,0]
	v_exp_f32_e32 v244, v244
	v_exp_f32_e32 v245, v245
	s_nop 0
	v_pk_add_f32 v[244:245], v[244:245], 1.0 op_sel_hi:[1,0]
	v_rcp_f32_e32 v119, v244
	v_rcp_f32_e32 v120, v245
	v_fma_f32 v92, v82, v96, 0
	v_pk_mul_f32 v[246:247], v[74:75], s[100:101] op_sel_hi:[1,0]
	v_pk_mul_f32 v[246:247], v[74:75], v[246:247]
	v_pk_fma_f32 v[246:247], v[74:75], v[246:247], v[74:75]
	v_pk_mul_f32 v[246:247], v[246:247], s[100:101] op_sel:[0,1] op_sel_hi:[1,1]
	v_pk_mul_f32 v[246:247], v[246:247], v[248:249] op_sel_hi:[1,0]
	v_exp_f32_e32 v246, v246
	v_exp_f32_e32 v247, v247
	s_nop 0
	v_pk_add_f32 v[246:247], v[246:247], 1.0 op_sel_hi:[1,0]
	v_rcp_f32_e32 v86, v246
	v_fmac_f32_e32 v92, v83, v97
	v_fmac_f32_e32 v92, v84, v98
	v_fmac_f32_e32 v92, v85, v99
	v_rcp_f32_e32 v87, v247
	v_fmac_f32_e32 v92, v78, v100
	v_fmac_f32_e32 v92, v79, v101
	v_fmac_f32_e32 v92, v80, v119
	v_fmac_f32_e32 v92, v81, v120
	v_pk_mul_f32 v[238:239], v[76:77], s[100:101] op_sel_hi:[1,0]
	v_pk_mul_f32 v[238:239], v[76:77], v[238:239]
	v_pk_fma_f32 v[238:239], v[76:77], v[238:239], v[76:77]
	v_pk_mul_f32 v[238:239], v[238:239], s[100:101] op_sel:[0,1] op_sel_hi:[1,1]
	v_pk_mul_f32 v[238:239], v[238:239], v[248:249] op_sel_hi:[1,0]
	v_exp_f32_e32 v238, v238
	v_exp_f32_e32 v239, v239
	s_nop 0
	v_pk_add_f32 v[238:239], v[238:239], 1.0 op_sel_hi:[1,0]
	v_rcp_f32_e32 v88, v238
	v_pk_mul_f32 v[90:91], v[74:75], v[86:87]
	v_rcp_f32_e32 v89, v239
	v_add_f32_e32 v0, v92, v90
	v_add_f32_e32 v0, v91, v0
	v_pk_mul_f32 v[90:91], v[76:77], v[88:89]
	v_add_f32_e32 v0, v90, v0
	v_add_f32_e32 v0, v91, v0
	v_pk_mul_f32 v[240:241], v[70:71], s[100:101] op_sel_hi:[1,0]
	v_pk_mul_f32 v[240:241], v[70:71], v[240:241]
	v_pk_fma_f32 v[240:241], v[70:71], v[240:241], v[70:71]
	v_pk_mul_f32 v[240:241], v[240:241], s[100:101] op_sel:[0,1] op_sel_hi:[1,1]
	v_pk_mul_f32 v[240:241], v[240:241], v[248:249] op_sel_hi:[1,0]
	v_exp_f32_e32 v240, v240
	v_exp_f32_e32 v241, v241
	s_nop 0
	v_pk_add_f32 v[240:241], v[240:241], 1.0 op_sel_hi:[1,0]
	v_rcp_f32_e32 v90, v240
	v_rcp_f32_e32 v91, v241
	v_pk_mul_f32 v[242:243], v[72:73], s[100:101] op_sel_hi:[1,0]
	v_pk_mul_f32 v[242:243], v[72:73], v[242:243]
	v_pk_fma_f32 v[242:243], v[72:73], v[242:243], v[72:73]
	v_pk_mul_f32 v[242:243], v[242:243], s[100:101] op_sel:[0,1] op_sel_hi:[1,1]
	v_pk_mul_f32 v[242:243], v[242:243], v[248:249] op_sel_hi:[1,0]
	v_exp_f32_e32 v242, v242
	v_exp_f32_e32 v243, v243
	s_nop 0
	v_pk_add_f32 v[242:243], v[242:243], 1.0 op_sel_hi:[1,0]
	v_rcp_f32_e32 v92, v242
	v_rcp_f32_e32 v93, v243
	v_pk_mul_f32 v[94:95], v[70:71], v[90:91]
	s_mov_b64 s[8:9], 0
	v_add_f32_e32 v0, v94, v0
	v_add_f32_e32 v0, v95, v0
	v_pk_mul_f32 v[94:95], v[72:73], v[92:93]
	s_nop 0
	v_add_f32_e32 v0, v94, v0
	v_add_f32_e32 v0, v95, v0
	v_and_b32_e32 v95, 64, v224
	v_xor_b32_e32 v94, 16, v224
	v_add_u32_e32 v95, 64, v95
	v_cmp_lt_i32_e32 vcc, v94, v95
	s_nop 1
	v_cndmask_b32_e32 v94, v224, v94, vcc
	v_lshlrev_b32_e32 v121, 2, v94
	ds_bpermute_b32 v94, v121, v0
	s_waitcnt lgkmcnt(0)
	v_add_f32_e32 v0, v0, v94
	v_xor_b32_e32 v94, 32, v224
	v_cmp_lt_i32_e32 vcc, v94, v95
	s_nop 1
	v_cndmask_b32_e32 v94, v224, v94, vcc
	v_lshlrev_b32_e32 v122, 2, v94
	ds_bpermute_b32 v94, v122, v0
	s_waitcnt lgkmcnt(0)
	v_add_f32_e32 v0, v0, v94
	v_mul_f32_e32 v0, 0x3c800000, v0
	v_fma_f32 v124, v83, v97, -v0
	v_fma_f32 v123, v82, v96, -v0
	v_mul_f32_e32 v96, v124, v124
	v_fmac_f32_e32 v96, v123, v123
	v_fma_f32 v98, v84, v98, -v0
	v_fmac_f32_e32 v96, v98, v98
	v_fma_f32 v99, v85, v99, -v0
	v_fmac_f32_e32 v96, v99, v99
	v_fma_f32 v100, v78, v100, -v0
	v_fmac_f32_e32 v96, v100, v100
	v_fma_f32 v101, v79, v101, -v0
	v_fmac_f32_e32 v96, v101, v101
	v_fma_f32 v125, v80, v119, -v0
	v_fmac_f32_e32 v96, v125, v125
	v_fma_f32 v120, v81, v120, -v0
	v_pk_fma_f32 v[94:95], v[74:75], v[86:87], v[0:1] op_sel_hi:[1,1,0] neg_lo:[0,0,1] neg_hi:[0,0,1]
	v_fmac_f32_e32 v96, v120, v120
	v_pk_mul_f32 v[86:87], v[94:95], v[94:95]
	v_pk_fma_f32 v[90:91], v[70:71], v[90:91], v[0:1] op_sel_hi:[1,1,0] neg_lo:[0,0,1] neg_hi:[0,0,1]
	v_add_f32_e32 v86, v86, v96
	v_pk_fma_f32 v[96:97], v[76:77], v[88:89], v[0:1] op_sel_hi:[1,1,0] neg_lo:[0,0,1] neg_hi:[0,0,1]
	v_add_f32_e32 v119, v87, v86
	v_pk_mul_f32 v[86:87], v[96:97], v[96:97]
	v_pk_fma_f32 v[92:93], v[72:73], v[92:93], v[0:1] op_sel_hi:[1,1,0] neg_lo:[0,0,1] neg_hi:[0,0,1]
	v_add_f32_e32 v86, v86, v119
	v_add_f32_e32 v88, v87, v86
	v_pk_mul_f32 v[86:87], v[90:91], v[90:91]
	v_ashrrev_i32_e32 v119, 31, v118
	v_add_f32_e32 v86, v86, v88
	v_add_f32_e32 v88, v87, v86
	v_pk_mul_f32 v[86:87], v[92:93], v[92:93]
	s_nop 0
	v_add_f32_e32 v0, v86, v88
	v_add_f32_e32 v0, v87, v0
	ds_bpermute_b32 v86, v121, v0
	s_waitcnt lgkmcnt(0)
	v_add_f32_e32 v0, v0, v86
	ds_bpermute_b32 v86, v122, v0
	s_waitcnt lgkmcnt(0)
	v_add_f32_e32 v0, v0, v86
	v_fmamk_f32 v0, v0, 0x3c800000, v222
	v_mul_f32_e32 v86, 0x4b800000, v0
	v_cmp_gt_f32_e32 vcc, s14, v0
	s_nop 1
	v_cndmask_b32_e32 v0, v0, v86, vcc
	v_rsq_f32_e32 v0, v0
	s_nop 0
	v_mul_f32_e32 v86, 0x45800000, v0
	v_cndmask_b32_e32 v0, v0, v86, vcc
	v_lshlrev_b64 v[86:87], 9, v[118:119]
	v_mul_f32_e32 v88, v123, v0
	v_mul_f32_e32 v89, v124, v0
	v_mul_f32_e32 v119, v98, v0
	v_mul_f32_e32 v121, v99, v0
	v_mul_f32_e32 v100, v100, v0
	v_mul_f32_e32 v101, v101, v0
	v_mul_f32_e32 v122, v125, v0
	v_mul_f32_e32 v120, v120, v0
	v_lshl_add_u64 v[98:99], v[196:197], 0, v[86:87]
	v_cvt_pk_bf16_f32 v86, v88, v89
	v_cvt_pk_bf16_f32 v87, v119, v121
	v_cvt_pk_bf16_f32 v88, v100, v101
	v_cvt_pk_bf16_f32 v89, v122, v120
	global_store_dwordx4 v[98:99], v[86:89], off
	v_mul_f32_e32 v90, v90, v0
	v_mul_f32_e32 v91, v91, v0
	v_mul_f32_e32 v86, v94, v0
	v_mul_f32_e32 v87, v95, v0
	v_mul_f32_e32 v88, v96, v0
	v_mul_f32_e32 v89, v97, v0
	v_mul_f32_e32 v92, v92, v0
	v_mul_f32_e32 v0, v93, v0
	v_cvt_pk_bf16_f32 v86, v86, v87
	v_cvt_pk_bf16_f32 v87, v88, v89
	v_cvt_pk_bf16_f32 v88, v90, v91
	v_cvt_pk_bf16_f32 v89, v92, v0
	global_store_dwordx4 v[98:99], v[86:89], off offset:64

.LBB0_453:
	v_add_u32_e32 v102, s29, v181
	s_mov_b64 s[44:45], -1
	s_mov_b64 s[0:1], 0
	s_cmp_lt_i32 s13, 1
	s_mov_b64 s[8:9], 0
	s_cbranch_scc1 .LBB0_457
	s_cmp_eq_u32 s13, 1
	s_mov_b64 s[8:9], -1
	s_cbranch_scc0 .LBB0_456
	s_mov_b32 s100, 0x3d372713
	s_mov_b32 s101, 0x3f4c422a
	v_mov_b32_e32 v248, 0xc038aa3b
	v_pk_mul_f32 v[238:239], v[66:67], s[100:101] op_sel_hi:[1,0]
	v_pk_mul_f32 v[238:239], v[66:67], v[238:239]
	v_pk_fma_f32 v[238:239], v[66:67], v[238:239], v[66:67]
	v_pk_mul_f32 v[238:239], v[238:239], s[100:101] op_sel:[0,1] op_sel_hi:[1,1]
	v_pk_mul_f32 v[238:239], v[238:239], v[248:249] op_sel_hi:[1,0]
	v_exp_f32_e32 v238, v238
	v_exp_f32_e32 v239, v239
	s_nop 0
	v_pk_add_f32 v[238:239], v[238:239], 1.0 op_sel_hi:[1,0]
	v_rcp_f32_e32 v80, v238
	v_rcp_f32_e32 v81, v239
	v_pk_mul_f32 v[240:241], v[68:69], s[100:101] op_sel_hi:[1,0]
	v_pk_mul_f32 v[240:241], v[68:69], v[240:241]
	v_pk_fma_f32 v[240:241], v[68:69], v[240:241], v[68:69]
	v_pk_mul_f32 v[240:241], v[240:241], s[100:101] op_sel:[0,1] op_sel_hi:[1,1]
	v_pk_mul_f32 v[240:241], v[240:241], v[248:249] op_sel_hi:[1,0]
	v_exp_f32_e32 v240, v240
	v_exp_f32_e32 v241, v241
	s_nop 0
	v_pk_add_f32 v[240:241], v[240:241], 1.0 op_sel_hi:[1,0]
	v_rcp_f32_e32 v82, v240
	v_rcp_f32_e32 v83, v241
	v_pk_mul_f32 v[242:243], v[62:63], s[100:101] op_sel_hi:[1,0]
	v_pk_mul_f32 v[242:243], v[62:63], v[242:243]
	v_pk_fma_f32 v[242:243], v[62:63], v[242:243], v[62:63]
	v_pk_mul_f32 v[242:243], v[242:243], s[100:101] op_sel:[0,1] op_sel_hi:[1,1]
	v_pk_mul_f32 v[242:243], v[242:243], v[248:249] op_sel_hi:[1,0]
	v_exp_f32_e32 v242, v242
	v_exp_f32_e32 v243, v243
	s_nop 0
	v_pk_add_f32 v[242:243], v[242:243], 1.0 op_sel_hi:[1,0]
	v_rcp_f32_e32 v84, v242
	v_rcp_f32_e32 v85, v243
	v_pk_mul_f32 v[244:245], v[64:65], s[100:101] op_sel_hi:[1,0]
	v_pk_mul_f32 v[244:245], v[64:65], v[244:245]
	v_pk_fma_f32 v[244:245], v[64:65], v[244:245], v[64:65]
	v_pk_mul_f32 v[244:245], v[244:245], s[100:101] op_sel:[0,1] op_sel_hi:[1,1]
	v_pk_mul_f32 v[244:245], v[244:245], v[248:249] op_sel_hi:[1,0]
	v_exp_f32_e32 v244, v244
	v_exp_f32_e32 v245, v245
	s_nop 0
	v_pk_add_f32 v[244:245], v[244:245], 1.0 op_sel_hi:[1,0]
	v_rcp_f32_e32 v103, v244
	v_rcp_f32_e32 v104, v245
	v_fma_f32 v76, v66, v80, 0
	v_pk_mul_f32 v[246:247], v[58:59], s[100:101] op_sel_hi:[1,0]
	v_pk_mul_f32 v[246:247], v[58:59], v[246:247]
	v_pk_fma_f32 v[246:247], v[58:59], v[246:247], v[58:59]
	v_pk_mul_f32 v[246:247], v[246:247], s[100:101] op_sel:[0,1] op_sel_hi:[1,1]
	v_pk_mul_f32 v[246:247], v[246:247], v[248:249] op_sel_hi:[1,0]
	v_exp_f32_e32 v246, v246
	v_exp_f32_e32 v247, v247
	s_nop 0
	v_pk_add_f32 v[246:247], v[246:247], 1.0 op_sel_hi:[1,0]
	v_rcp_f32_e32 v70, v246
	v_fmac_f32_e32 v76, v67, v81
	v_fmac_f32_e32 v76, v68, v82
	v_fmac_f32_e32 v76, v69, v83
	v_rcp_f32_e32 v71, v247
	v_fmac_f32_e32 v76, v62, v84
	v_fmac_f32_e32 v76, v63, v85
	v_fmac_f32_e32 v76, v64, v103
	v_fmac_f32_e32 v76, v65, v104
	v_pk_mul_f32 v[238:239], v[60:61], s[100:101] op_sel_hi:[1,0]
	v_pk_mul_f32 v[238:239], v[60:61], v[238:239]
	v_pk_fma_f32 v[238:239], v[60:61], v[238:239], v[60:61]
	v_pk_mul_f32 v[238:239], v[238:239], s[100:101] op_sel:[0,1] op_sel_hi:[1,1]
	v_pk_mul_f32 v[238:239], v[238:239], v[248:249] op_sel_hi:[1,0]
	v_exp_f32_e32 v238, v238
	v_exp_f32_e32 v239, v239
	s_nop 0
	v_pk_add_f32 v[238:239], v[238:239], 1.0 op_sel_hi:[1,0]
	v_rcp_f32_e32 v72, v238
	v_pk_mul_f32 v[74:75], v[58:59], v[70:71]
	v_rcp_f32_e32 v73, v239
	v_add_f32_e32 v0, v76, v74
	v_add_f32_e32 v0, v75, v0
	v_pk_mul_f32 v[74:75], v[60:61], v[72:73]
	v_add_f32_e32 v0, v74, v0
	v_add_f32_e32 v0, v75, v0
	v_pk_mul_f32 v[240:241], v[54:55], s[100:101] op_sel_hi:[1,0]
	v_pk_mul_f32 v[240:241], v[54:55], v[240:241]
	v_pk_fma_f32 v[240:241], v[54:55], v[240:241], v[54:55]
	v_pk_mul_f32 v[240:241], v[240:241], s[100:101] op_sel:[0,1] op_sel_hi:[1,1]
	v_pk_mul_f32 v[240:241], v[240:241], v[248:249] op_sel_hi:[1,0]
	v_exp_f32_e32 v240, v240
	v_exp_f32_e32 v241, v241
	s_nop 0
	v_pk_add_f32 v[240:241], v[240:241], 1.0 op_sel_hi:[1,0]
	v_rcp_f32_e32 v74, v240
	v_rcp_f32_e32 v75, v241
	v_pk_mul_f32 v[242:243], v[56:57], s[100:101] op_sel_hi:[1,0]
	v_pk_mul_f32 v[242:243], v[56:57], v[242:243]
	v_pk_fma_f32 v[242:243], v[56:57], v[242:243], v[56:57]
	v_pk_mul_f32 v[242:243], v[242:243], s[100:101] op_sel:[0,1] op_sel_hi:[1,1]
	v_pk_mul_f32 v[242:243], v[242:243], v[248:249] op_sel_hi:[1,0]
	v_exp_f32_e32 v242, v242
	v_exp_f32_e32 v243, v243
	s_nop 0
	v_pk_add_f32 v[242:243], v[242:243], 1.0 op_sel_hi:[1,0]
	v_rcp_f32_e32 v76, v242
	v_rcp_f32_e32 v77, v243
	v_pk_mul_f32 v[78:79], v[54:55], v[74:75]
	s_mov_b64 s[8:9], 0
	v_add_f32_e32 v0, v78, v0
	v_add_f32_e32 v0, v79, v0
	v_pk_mul_f32 v[78:79], v[56:57], v[76:77]
	s_nop 0
	v_add_f32_e32 v0, v78, v0
	v_add_f32_e32 v0, v79, v0
	v_and_b32_e32 v79, 64, v224
	v_xor_b32_e32 v78, 16, v224
	v_add_u32_e32 v79, 64, v79
	v_cmp_lt_i32_e32 vcc, v78, v79
	s_nop 1
	v_cndmask_b32_e32 v78, v224, v78, vcc
	v_lshlrev_b32_e32 v105, 2, v78
	ds_bpermute_b32 v78, v105, v0
	s_waitcnt lgkmcnt(0)
	v_add_f32_e32 v0, v0, v78
	v_xor_b32_e32 v78, 32, v224
	v_cmp_lt_i32_e32 vcc, v78, v79
	s_nop 1
	v_cndmask_b32_e32 v78, v224, v78, vcc
	v_lshlrev_b32_e32 v106, 2, v78
	ds_bpermute_b32 v78, v106, v0
	s_waitcnt lgkmcnt(0)
	v_add_f32_e32 v0, v0, v78
	v_mul_f32_e32 v0, 0x3c800000, v0
	v_fma_f32 v108, v67, v81, -v0
	v_fma_f32 v107, v66, v80, -v0
	v_mul_f32_e32 v80, v108, v108
	v_fmac_f32_e32 v80, v107, v107
	v_fma_f32 v82, v68, v82, -v0
	v_fmac_f32_e32 v80, v82, v82
	v_fma_f32 v83, v69, v83, -v0
	v_fmac_f32_e32 v80, v83, v83
	v_fma_f32 v84, v62, v84, -v0
	v_fmac_f32_e32 v80, v84, v84
	v_fma_f32 v85, v63, v85, -v0
	v_fmac_f32_e32 v80, v85, v85
	v_fma_f32 v109, v64, v103, -v0
	v_fmac_f32_e32 v80, v109, v109
	v_fma_f32 v104, v65, v104, -v0
	v_pk_fma_f32 v[78:79], v[58:59], v[70:71], v[0:1] op_sel_hi:[1,1,0] neg_lo:[0,0,1] neg_hi:[0,0,1]
	v_fmac_f32_e32 v80, v104, v104
	v_pk_mul_f32 v[70:71], v[78:79], v[78:79]
	v_pk_fma_f32 v[74:75], v[54:55], v[74:75], v[0:1] op_sel_hi:[1,1,0] neg_lo:[0,0,1] neg_hi:[0,0,1]
	v_add_f32_e32 v70, v70, v80
	v_pk_fma_f32 v[80:81], v[60:61], v[72:73], v[0:1] op_sel_hi:[1,1,0] neg_lo:[0,0,1] neg_hi:[0,0,1]
	v_add_f32_e32 v103, v71, v70
	v_pk_mul_f32 v[70:71], v[80:81], v[80:81]
	v_pk_fma_f32 v[76:77], v[56:57], v[76:77], v[0:1] op_sel_hi:[1,1,0] neg_lo:[0,0,1] neg_hi:[0,0,1]
	v_add_f32_e32 v70, v70, v103
	v_add_f32_e32 v72, v71, v70
	v_pk_mul_f32 v[70:71], v[74:75], v[74:75]
	v_ashrrev_i32_e32 v103, 31, v102
	v_add_f32_e32 v70, v70, v72
	v_add_f32_e32 v72, v71, v70
	v_pk_mul_f32 v[70:71], v[76:77], v[76:77]
	s_nop 0
	v_add_f32_e32 v0, v70, v72
	v_add_f32_e32 v0, v71, v0
	ds_bpermute_b32 v70, v105, v0
	s_waitcnt lgkmcnt(0)
	v_add_f32_e32 v0, v0, v70
	ds_bpermute_b32 v70, v106, v0
	s_waitcnt lgkmcnt(0)
	v_add_f32_e32 v0, v0, v70
	v_fmamk_f32 v0, v0, 0x3c800000, v222
	v_mul_f32_e32 v70, 0x4b800000, v0
	v_cmp_gt_f32_e32 vcc, s14, v0
	s_nop 1
	v_cndmask_b32_e32 v0, v0, v70, vcc
	v_rsq_f32_e32 v0, v0
	s_nop 0
	v_mul_f32_e32 v70, 0x45800000, v0
	v_cndmask_b32_e32 v0, v0, v70, vcc
	v_lshlrev_b64 v[70:71], 9, v[102:103]
	v_mul_f32_e32 v72, v107, v0
	v_mul_f32_e32 v73, v108, v0
	v_mul_f32_e32 v103, v82, v0
	v_mul_f32_e32 v105, v83, v0
	v_mul_f32_e32 v84, v84, v0
	v_mul_f32_e32 v85, v85, v0
	v_mul_f32_e32 v106, v109, v0
	v_mul_f32_e32 v104, v104, v0
	v_lshl_add_u64 v[82:83], v[196:197], 0, v[70:71]
	v_cvt_pk_bf16_f32 v70, v72, v73
	v_cvt_pk_bf16_f32 v71, v103, v105
	v_cvt_pk_bf16_f32 v72, v84, v85
	v_cvt_pk_bf16_f32 v73, v106, v104
	global_store_dwordx4 v[82:83], v[70:73], off
	v_mul_f32_e32 v74, v74, v0
	v_mul_f32_e32 v75, v75, v0
	v_mul_f32_e32 v70, v78, v0
	v_mul_f32_e32 v71, v79, v0
	v_mul_f32_e32 v72, v80, v0
	v_mul_f32_e32 v73, v81, v0
	v_mul_f32_e32 v76, v76, v0
	v_mul_f32_e32 v0, v77, v0
	v_cvt_pk_bf16_f32 v70, v70, v71
	v_cvt_pk_bf16_f32 v71, v72, v73
	v_cvt_pk_bf16_f32 v72, v74, v75
	v_cvt_pk_bf16_f32 v73, v76, v0
	global_store_dwordx4 v[82:83], v[70:73], off offset:64

.LBB0_499:
	v_add_u32_e32 v86, s29, v183
	s_mov_b64 s[44:45], -1
	s_mov_b64 s[0:1], 0
	s_cmp_lt_i32 s13, 1
	s_mov_b64 s[8:9], 0
	s_cbranch_scc1 .LBB0_503
	s_cmp_eq_u32 s13, 1
	s_mov_b64 s[8:9], -1
	s_cbranch_scc0 .LBB0_502
	s_mov_b32 s100, 0x3d372713
	s_mov_b32 s101, 0x3f4c422a
	v_mov_b32_e32 v248, 0xc038aa3b
	v_pk_mul_f32 v[238:239], v[50:51], s[100:101] op_sel_hi:[1,0]
	v_pk_mul_f32 v[238:239], v[50:51], v[238:239]
	v_pk_fma_f32 v[238:239], v[50:51], v[238:239], v[50:51]
	v_pk_mul_f32 v[238:239], v[238:239], s[100:101] op_sel:[0,1] op_sel_hi:[1,1]
	v_pk_mul_f32 v[238:239], v[238:239], v[248:249] op_sel_hi:[1,0]
	v_exp_f32_e32 v238, v238
	v_exp_f32_e32 v239, v239
	s_nop 0
	v_pk_add_f32 v[238:239], v[238:239], 1.0 op_sel_hi:[1,0]
	v_rcp_f32_e32 v64, v238
	v_rcp_f32_e32 v65, v239
	v_pk_mul_f32 v[240:241], v[52:53], s[100:101] op_sel_hi:[1,0]
	v_pk_mul_f32 v[240:241], v[52:53], v[240:241]
	v_pk_fma_f32 v[240:241], v[52:53], v[240:241], v[52:53]
	v_pk_mul_f32 v[240:241], v[240:241], s[100:101] op_sel:[0,1] op_sel_hi:[1,1]
	v_pk_mul_f32 v[240:241], v[240:241], v[248:249] op_sel_hi:[1,0]
	v_exp_f32_e32 v240, v240
	v_exp_f32_e32 v241, v241
	s_nop 0
	v_pk_add_f32 v[240:241], v[240:241], 1.0 op_sel_hi:[1,0]
	v_rcp_f32_e32 v66, v240
	v_rcp_f32_e32 v67, v241
	v_pk_mul_f32 v[242:243], v[46:47], s[100:101] op_sel_hi:[1,0]
	v_pk_mul_f32 v[242:243], v[46:47], v[242:243]
	v_pk_fma_f32 v[242:243], v[46:47], v[242:243], v[46:47]
	v_pk_mul_f32 v[242:243], v[242:243], s[100:101] op_sel:[0,1] op_sel_hi:[1,1]
	v_pk_mul_f32 v[242:243], v[242:243], v[248:249] op_sel_hi:[1,0]
	v_exp_f32_e32 v242, v242
	v_exp_f32_e32 v243, v243
	s_nop 0
	v_pk_add_f32 v[242:243], v[242:243], 1.0 op_sel_hi:[1,0]
	v_rcp_f32_e32 v68, v242
	v_rcp_f32_e32 v69, v243
	v_pk_mul_f32 v[244:245], v[48:49], s[100:101] op_sel_hi:[1,0]
	v_pk_mul_f32 v[244:245], v[48:49], v[244:245]
	v_pk_fma_f32 v[244:245], v[48:49], v[244:245], v[48:49]
	v_pk_mul_f32 v[244:245], v[244:245], s[100:101] op_sel:[0,1] op_sel_hi:[1,1]
	v_pk_mul_f32 v[244:245], v[244:245], v[248:249] op_sel_hi:[1,0]
	v_exp_f32_e32 v244, v244
	v_exp_f32_e32 v245, v245
	s_nop 0
	v_pk_add_f32 v[244:245], v[244:245], 1.0 op_sel_hi:[1,0]
	v_rcp_f32_e32 v87, v244
	v_rcp_f32_e32 v88, v245
	v_fma_f32 v60, v50, v64, 0
	v_pk_mul_f32 v[246:247], v[42:43], s[100:101] op_sel_hi:[1,0]
	v_pk_mul_f32 v[246:247], v[42:43], v[246:247]
	v_pk_fma_f32 v[246:247], v[42:43], v[246:247], v[42:43]
	v_pk_mul_f32 v[246:247], v[246:247], s[100:101] op_sel:[0,1] op_sel_hi:[1,1]
	v_pk_mul_f32 v[246:247], v[246:247], v[248:249] op_sel_hi:[1,0]
	v_exp_f32_e32 v246, v246
	v_exp_f32_e32 v247, v247
	s_nop 0
	v_pk_add_f32 v[246:247], v[246:247], 1.0 op_sel_hi:[1,0]
	v_rcp_f32_e32 v54, v246
	v_fmac_f32_e32 v60, v51, v65
	v_fmac_f32_e32 v60, v52, v66
	v_fmac_f32_e32 v60, v53, v67
	v_rcp_f32_e32 v55, v247
	v_fmac_f32_e32 v60, v46, v68
	v_fmac_f32_e32 v60, v47, v69
	v_fmac_f32_e32 v60, v48, v87
	v_fmac_f32_e32 v60, v49, v88
	v_pk_mul_f32 v[238:239], v[44:45], s[100:101] op_sel_hi:[1,0]
	v_pk_mul_f32 v[238:239], v[44:45], v[238:239]
	v_pk_fma_f32 v[238:239], v[44:45], v[238:239], v[44:45]
	v_pk_mul_f32 v[238:239], v[238:239], s[100:101] op_sel:[0,1] op_sel_hi:[1,1]
	v_pk_mul_f32 v[238:239], v[238:239], v[248:249] op_sel_hi:[1,0]
	v_exp_f32_e32 v238, v238
	v_exp_f32_e32 v239, v239
	s_nop 0
	v_pk_add_f32 v[238:239], v[238:239], 1.0 op_sel_hi:[1,0]
	v_rcp_f32_e32 v56, v238
	v_pk_mul_f32 v[58:59], v[42:43], v[54:55]
	v_rcp_f32_e32 v57, v239
	v_add_f32_e32 v0, v60, v58
	v_add_f32_e32 v0, v59, v0
	v_pk_mul_f32 v[58:59], v[44:45], v[56:57]
	v_add_f32_e32 v0, v58, v0
	v_add_f32_e32 v0, v59, v0
	v_pk_mul_f32 v[240:241], v[30:31], s[100:101] op_sel_hi:[1,0]
	v_pk_mul_f32 v[240:241], v[30:31], v[240:241]
	v_pk_fma_f32 v[240:241], v[30:31], v[240:241], v[30:31]
	v_pk_mul_f32 v[240:241], v[240:241], s[100:101] op_sel:[0,1] op_sel_hi:[1,1]
	v_pk_mul_f32 v[240:241], v[240:241], v[248:249] op_sel_hi:[1,0]
	v_exp_f32_e32 v240, v240
	v_exp_f32_e32 v241, v241
	s_nop 0
	v_pk_add_f32 v[240:241], v[240:241], 1.0 op_sel_hi:[1,0]
	v_rcp_f32_e32 v58, v240
	v_rcp_f32_e32 v59, v241
	v_pk_mul_f32 v[242:243], v[32:33], s[100:101] op_sel_hi:[1,0]
	v_pk_mul_f32 v[242:243], v[32:33], v[242:243]
	v_pk_fma_f32 v[242:243], v[32:33], v[242:243], v[32:33]
	v_pk_mul_f32 v[242:243], v[242:243], s[100:101] op_sel:[0,1] op_sel_hi:[1,1]
	v_pk_mul_f32 v[242:243], v[242:243], v[248:249] op_sel_hi:[1,0]
	v_exp_f32_e32 v242, v242
	v_exp_f32_e32 v243, v243
	s_nop 0
	v_pk_add_f32 v[242:243], v[242:243], 1.0 op_sel_hi:[1,0]
	v_rcp_f32_e32 v60, v242
	v_rcp_f32_e32 v61, v243
	v_pk_mul_f32 v[62:63], v[30:31], v[58:59]
	s_mov_b64 s[8:9], 0
	v_add_f32_e32 v0, v62, v0
	v_add_f32_e32 v0, v63, v0
	v_pk_mul_f32 v[62:63], v[32:33], v[60:61]
	s_nop 0
	v_add_f32_e32 v0, v62, v0
	v_add_f32_e32 v0, v63, v0
	v_and_b32_e32 v63, 64, v224
	v_xor_b32_e32 v62, 16, v224
	v_add_u32_e32 v63, 64, v63
	v_cmp_lt_i32_e32 vcc, v62, v63
	s_nop 1
	v_cndmask_b32_e32 v62, v224, v62, vcc
	v_lshlrev_b32_e32 v89, 2, v62
	ds_bpermute_b32 v62, v89, v0
	s_waitcnt lgkmcnt(0)
	v_add_f32_e32 v0, v0, v62
	v_xor_b32_e32 v62, 32, v224
	v_cmp_lt_i32_e32 vcc, v62, v63
	s_nop 1
	v_cndmask_b32_e32 v62, v224, v62, vcc
	v_lshlrev_b32_e32 v90, 2, v62
	ds_bpermute_b32 v62, v90, v0
	s_waitcnt lgkmcnt(0)
	v_add_f32_e32 v0, v0, v62
	v_mul_f32_e32 v0, 0x3c800000, v0
	v_fma_f32 v92, v51, v65, -v0
	v_fma_f32 v91, v50, v64, -v0
	v_mul_f32_e32 v64, v92, v92
	v_fmac_f32_e32 v64, v91, v91
	v_fma_f32 v66, v52, v66, -v0
	v_fmac_f32_e32 v64, v66, v66
	v_fma_f32 v67, v53, v67, -v0
	v_fmac_f32_e32 v64, v67, v67
	v_fma_f32 v68, v46, v68, -v0
	v_fmac_f32_e32 v64, v68, v68
	v_fma_f32 v69, v47, v69, -v0
	v_fmac_f32_e32 v64, v69, v69
	v_fma_f32 v93, v48, v87, -v0
	v_fmac_f32_e32 v64, v93, v93
	v_fma_f32 v88, v49, v88, -v0
	v_pk_fma_f32 v[62:63], v[42:43], v[54:55], v[0:1] op_sel_hi:[1,1,0] neg_lo:[0,0,1] neg_hi:[0,0,1]
	v_fmac_f32_e32 v64, v88, v88
	v_pk_mul_f32 v[54:55], v[62:63], v[62:63]
	v_pk_fma_f32 v[58:59], v[30:31], v[58:59], v[0:1] op_sel_hi:[1,1,0] neg_lo:[0,0,1] neg_hi:[0,0,1]
	v_add_f32_e32 v54, v54, v64
	v_pk_fma_f32 v[64:65], v[44:45], v[56:57], v[0:1] op_sel_hi:[1,1,0] neg_lo:[0,0,1] neg_hi:[0,0,1]
	v_add_f32_e32 v87, v55, v54
	v_pk_mul_f32 v[54:55], v[64:65], v[64:65]
	v_pk_fma_f32 v[60:61], v[32:33], v[60:61], v[0:1] op_sel_hi:[1,1,0] neg_lo:[0,0,1] neg_hi:[0,0,1]
	v_add_f32_e32 v54, v54, v87
	v_add_f32_e32 v56, v55, v54
	v_pk_mul_f32 v[54:55], v[58:59], v[58:59]
	v_ashrrev_i32_e32 v87, 31, v86
	v_add_f32_e32 v54, v54, v56
	v_add_f32_e32 v56, v55, v54
	v_pk_mul_f32 v[54:55], v[60:61], v[60:61]
	s_nop 0
	v_add_f32_e32 v0, v54, v56
	v_add_f32_e32 v0, v55, v0
	ds_bpermute_b32 v54, v89, v0
	s_waitcnt lgkmcnt(0)
	v_add_f32_e32 v0, v0, v54
	ds_bpermute_b32 v54, v90, v0
	s_waitcnt lgkmcnt(0)
	v_add_f32_e32 v0, v0, v54
	v_fmamk_f32 v0, v0, 0x3c800000, v222
	v_mul_f32_e32 v54, 0x4b800000, v0
	v_cmp_gt_f32_e32 vcc, s14, v0
	s_nop 1
	v_cndmask_b32_e32 v0, v0, v54, vcc
	v_rsq_f32_e32 v0, v0
	s_nop 0
	v_mul_f32_e32 v54, 0x45800000, v0
	v_cndmask_b32_e32 v0, v0, v54, vcc
	v_lshlrev_b64 v[54:55], 9, v[86:87]
	v_mul_f32_e32 v56, v91, v0
	v_mul_f32_e32 v57, v92, v0
	v_mul_f32_e32 v87, v66, v0
	v_mul_f32_e32 v89, v67, v0
	v_mul_f32_e32 v68, v68, v0
	v_mul_f32_e32 v69, v69, v0
	v_mul_f32_e32 v90, v93, v0
	v_mul_f32_e32 v88, v88, v0
	v_lshl_add_u64 v[66:67], v[196:197], 0, v[54:55]
	v_cvt_pk_bf16_f32 v54, v56, v57
	v_cvt_pk_bf16_f32 v55, v87, v89
	v_cvt_pk_bf16_f32 v56, v68, v69
	v_cvt_pk_bf16_f32 v57, v90, v88
	global_store_dwordx4 v[66:67], v[54:57], off
	v_mul_f32_e32 v58, v58, v0
	v_mul_f32_e32 v59, v59, v0
	v_mul_f32_e32 v54, v62, v0
	v_mul_f32_e32 v55, v63, v0
	v_mul_f32_e32 v56, v64, v0
	v_mul_f32_e32 v57, v65, v0
	v_mul_f32_e32 v60, v60, v0
	v_mul_f32_e32 v0, v61, v0
	v_cvt_pk_bf16_f32 v54, v54, v55
	v_cvt_pk_bf16_f32 v55, v56, v57
	v_cvt_pk_bf16_f32 v56, v58, v59
	v_cvt_pk_bf16_f32 v57, v60, v0
	global_store_dwordx4 v[66:67], v[54:57], off offset:64

.LBB0_553:
	s_cmp_eq_u32 s13, 1
	s_mov_b64 s[8:9], -1
	s_cbranch_scc0 .LBB0_555
	s_mov_b32 s100, 0x3d372713
	s_mov_b32 s101, 0x3f4c422a
	v_mov_b32_e32 v248, 0xc038aa3b
	v_pk_mul_f32 v[238:239], v[18:19], s[100:101] op_sel_hi:[1,0]
	v_pk_mul_f32 v[238:239], v[18:19], v[238:239]
	v_pk_fma_f32 v[238:239], v[18:19], v[238:239], v[18:19]
	v_pk_mul_f32 v[238:239], v[238:239], s[100:101] op_sel:[0,1] op_sel_hi:[1,1]
	v_pk_mul_f32 v[238:239], v[238:239], v[248:249] op_sel_hi:[1,0]
	v_exp_f32_e32 v238, v238
	v_exp_f32_e32 v239, v239
	s_nop 0
	v_pk_add_f32 v[238:239], v[238:239], 1.0 op_sel_hi:[1,0]
	v_rcp_f32_e32 v50, v238
	v_rcp_f32_e32 v51, v239
	v_pk_mul_f32 v[240:241], v[20:21], s[100:101] op_sel_hi:[1,0]
	v_pk_mul_f32 v[240:241], v[20:21], v[240:241]
	v_pk_fma_f32 v[240:241], v[20:21], v[240:241], v[20:21]
	v_pk_mul_f32 v[240:241], v[240:241], s[100:101] op_sel:[0,1] op_sel_hi:[1,1]
	v_pk_mul_f32 v[240:241], v[240:241], v[248:249] op_sel_hi:[1,0]
	v_exp_f32_e32 v240, v240
	v_exp_f32_e32 v241, v241
	s_nop 0
	v_pk_add_f32 v[240:241], v[240:241], 1.0 op_sel_hi:[1,0]
	v_rcp_f32_e32 v52, v240
	v_rcp_f32_e32 v53, v241
	v_pk_mul_f32 v[242:243], v[14:15], s[100:101] op_sel_hi:[1,0]
	v_pk_mul_f32 v[242:243], v[14:15], v[242:243]
	v_pk_fma_f32 v[242:243], v[14:15], v[242:243], v[14:15]
	v_pk_mul_f32 v[242:243], v[242:243], s[100:101] op_sel:[0,1] op_sel_hi:[1,1]
	v_pk_mul_f32 v[242:243], v[242:243], v[248:249] op_sel_hi:[1,0]
	v_exp_f32_e32 v242, v242
	v_exp_f32_e32 v243, v243
	s_nop 0
	v_pk_add_f32 v[242:243], v[242:243], 1.0 op_sel_hi:[1,0]
	v_rcp_f32_e32 v70, v242
	v_rcp_f32_e32 v71, v243
	v_pk_mul_f32 v[244:245], v[16:17], s[100:101] op_sel_hi:[1,0]
	v_pk_mul_f32 v[244:245], v[16:17], v[244:245]
	v_pk_fma_f32 v[244:245], v[16:17], v[244:245], v[16:17]
	v_pk_mul_f32 v[244:245], v[244:245], s[100:101] op_sel:[0,1] op_sel_hi:[1,1]
	v_pk_mul_f32 v[244:245], v[244:245], v[248:249] op_sel_hi:[1,0]
	v_exp_f32_e32 v244, v244
	v_exp_f32_e32 v245, v245
	s_nop 0
	v_pk_add_f32 v[244:245], v[244:245], 1.0 op_sel_hi:[1,0]
	v_rcp_f32_e32 v72, v244
	v_rcp_f32_e32 v73, v245
	v_fma_f32 v31, v18, v50, 0
	v_pk_mul_f32 v[246:247], v[10:11], s[100:101] op_sel_hi:[1,0]
	v_pk_mul_f32 v[246:247], v[10:11], v[246:247]
	v_pk_fma_f32 v[246:247], v[10:11], v[246:247], v[10:11]
	v_pk_mul_f32 v[246:247], v[246:247], s[100:101] op_sel:[0,1] op_sel_hi:[1,1]
	v_pk_mul_f32 v[246:247], v[246:247], v[248:249] op_sel_hi:[1,0]
	v_exp_f32_e32 v246, v246
	v_exp_f32_e32 v247, v247
	s_nop 0
	v_pk_add_f32 v[246:247], v[246:247], 1.0 op_sel_hi:[1,0]
	v_rcp_f32_e32 v32, v246
	v_fmac_f32_e32 v31, v19, v51
	v_fmac_f32_e32 v31, v20, v52
	v_fmac_f32_e32 v31, v21, v53
	v_rcp_f32_e32 v33, v247
	v_fmac_f32_e32 v31, v14, v70
	v_pk_mul_f32 v[238:239], v[12:13], s[100:101] op_sel_hi:[1,0]
	v_pk_mul_f32 v[238:239], v[12:13], v[238:239]
	v_pk_fma_f32 v[238:239], v[12:13], v[238:239], v[12:13]
	v_pk_mul_f32 v[238:239], v[238:239], s[100:101] op_sel:[0,1] op_sel_hi:[1,1]
	v_pk_mul_f32 v[238:239], v[238:239], v[248:249] op_sel_hi:[1,0]
	v_exp_f32_e32 v238, v238
	v_exp_f32_e32 v239, v239
	s_nop 0
	v_pk_add_f32 v[238:239], v[238:239], 1.0 op_sel_hi:[1,0]
	v_rcp_f32_e32 v42, v238
	v_fmac_f32_e32 v31, v15, v71
	v_rcp_f32_e32 v43, v239
	v_fmac_f32_e32 v31, v16, v72
	v_fmac_f32_e32 v31, v17, v73
	v_pk_mul_f32 v[44:45], v[10:11], v[32:33]
	s_mov_b64 s[8:9], 0
	v_add_f32_e32 v0, v31, v44
	v_add_f32_e32 v0, v45, v0
	v_pk_mul_f32 v[44:45], v[12:13], v[42:43]
	v_add_f32_e32 v0, v44, v0
	v_add_f32_e32 v0, v45, v0
	v_pk_mul_f32 v[240:241], v[6:7], s[100:101] op_sel_hi:[1,0]
	v_pk_mul_f32 v[240:241], v[6:7], v[240:241]
	v_pk_fma_f32 v[240:241], v[6:7], v[240:241], v[6:7]
	v_pk_mul_f32 v[240:241], v[240:241], s[100:101] op_sel:[0,1] op_sel_hi:[1,1]
	v_pk_mul_f32 v[240:241], v[240:241], v[248:249] op_sel_hi:[1,0]
	v_exp_f32_e32 v240, v240
	v_exp_f32_e32 v241, v241
	s_nop 0
	v_pk_add_f32 v[240:241], v[240:241], 1.0 op_sel_hi:[1,0]
	v_rcp_f32_e32 v44, v240
	v_rcp_f32_e32 v45, v241
	v_pk_mul_f32 v[242:243], v[8:9], s[100:101] op_sel_hi:[1,0]
	v_pk_mul_f32 v[242:243], v[8:9], v[242:243]
	v_pk_fma_f32 v[242:243], v[8:9], v[242:243], v[8:9]
	v_pk_mul_f32 v[242:243], v[242:243], s[100:101] op_sel:[0,1] op_sel_hi:[1,1]
	v_pk_mul_f32 v[242:243], v[242:243], v[248:249] op_sel_hi:[1,0]
	v_exp_f32_e32 v242, v242
	v_exp_f32_e32 v243, v243
	s_nop 0
	v_pk_add_f32 v[242:243], v[242:243], 1.0 op_sel_hi:[1,0]
	v_rcp_f32_e32 v46, v242
	v_rcp_f32_e32 v47, v243
	v_pk_mul_f32 v[48:49], v[6:7], v[44:45]
	v_xor_b32_e32 v31, 16, v224
	v_add_f32_e32 v0, v48, v0
	v_add_f32_e32 v0, v49, v0
	v_pk_mul_f32 v[48:49], v[8:9], v[46:47]
	s_nop 0
	v_add_f32_e32 v0, v48, v0
	v_and_b32_e32 v48, 64, v224
	v_add_u32_e32 v48, 64, v48
	v_cmp_lt_i32_e32 vcc, v31, v48
	v_add_f32_e32 v0, v49, v0
	s_nop 0
	v_cndmask_b32_e32 v31, v224, v31, vcc
	v_lshlrev_b32_e32 v31, 2, v31
	ds_bpermute_b32 v49, v31, v0
	s_waitcnt lgkmcnt(0)
	v_add_f32_e32 v0, v0, v49
	v_xor_b32_e32 v49, 32, v224
	v_cmp_lt_i32_e32 vcc, v49, v48
	s_nop 1
	v_cndmask_b32_e32 v48, v224, v49, vcc
	v_lshlrev_b32_e32 v74, 2, v48
	ds_bpermute_b32 v48, v74, v0
	s_waitcnt lgkmcnt(0)
	v_add_f32_e32 v0, v0, v48
	v_mul_f32_e32 v0, 0x3c800000, v0
	v_fma_f32 v76, v19, v51, -v0
	v_fma_f32 v75, v18, v50, -v0
	v_mul_f32_e32 v50, v76, v76
	v_fmac_f32_e32 v50, v75, v75
	v_fma_f32 v52, v20, v52, -v0
	v_fmac_f32_e32 v50, v52, v52
	v_fma_f32 v53, v21, v53, -v0
	v_fmac_f32_e32 v50, v53, v53
	v_fma_f32 v70, v14, v70, -v0
	v_fmac_f32_e32 v50, v70, v70
	v_fma_f32 v71, v15, v71, -v0
	v_fmac_f32_e32 v50, v71, v71
	v_fma_f32 v72, v16, v72, -v0
	v_fmac_f32_e32 v50, v72, v72
	v_fma_f32 v73, v17, v73, -v0
	v_pk_fma_f32 v[32:33], v[10:11], v[32:33], v[0:1] op_sel_hi:[1,1,0] neg_lo:[0,0,1] neg_hi:[0,0,1]
	v_fmac_f32_e32 v50, v73, v73
	v_pk_mul_f32 v[48:49], v[32:33], v[32:33]
	v_pk_fma_f32 v[46:47], v[8:9], v[46:47], v[0:1] op_sel_hi:[1,1,0] neg_lo:[0,0,1] neg_hi:[0,0,1]
	v_add_f32_e32 v48, v48, v50
	v_add_f32_e32 v50, v49, v48
	v_pk_fma_f32 v[48:49], v[12:13], v[42:43], v[0:1] op_sel_hi:[1,1,0] neg_lo:[0,0,1] neg_hi:[0,0,1]
	s_nop 0
	v_pk_mul_f32 v[42:43], v[48:49], v[48:49]
	s_nop 0
	v_add_f32_e32 v42, v42, v50
	v_pk_fma_f32 v[50:51], v[6:7], v[44:45], v[0:1] op_sel_hi:[1,1,0] neg_lo:[0,0,1] neg_hi:[0,0,1]
	v_add_f32_e32 v77, v43, v42
	v_pk_mul_f32 v[42:43], v[50:51], v[50:51]
	s_nop 0
	v_add_f32_e32 v42, v42, v77
	v_add_f32_e32 v44, v43, v42
	v_pk_mul_f32 v[42:43], v[46:47], v[46:47]
	s_nop 0
	v_add_f32_e32 v0, v42, v44
	v_add_f32_e32 v0, v43, v0
	ds_bpermute_b32 v31, v31, v0
	s_waitcnt lgkmcnt(0)
	v_add_f32_e32 v0, v0, v31
	ds_bpermute_b32 v31, v74, v0
	s_waitcnt lgkmcnt(0)
	v_add_f32_e32 v0, v0, v31
	v_fmamk_f32 v0, v0, 0x3c800000, v222
	v_mul_f32_e32 v31, 0x4b800000, v0
	v_cmp_gt_f32_e32 vcc, s14, v0
	s_nop 1
	v_cndmask_b32_e32 v0, v0, v31, vcc
	v_rsq_f32_e32 v0, v0
	s_nop 0
	v_mul_f32_e32 v31, 0x45800000, v0
	v_cndmask_b32_e32 v0, v0, v31, vcc
	v_ashrrev_i32_e32 v31, 31, v30
	v_lshlrev_b64 v[42:43], 9, v[30:31]
	v_mul_f32_e32 v44, v76, v0
	v_mul_f32_e32 v45, v52, v0
	v_mul_f32_e32 v31, v75, v0
	v_mul_f32_e32 v74, v53, v0
	v_mul_f32_e32 v70, v70, v0
	v_mul_f32_e32 v71, v71, v0
	v_mul_f32_e32 v72, v72, v0
	v_mul_f32_e32 v73, v73, v0
	v_lshl_add_u64 v[52:53], v[196:197], 0, v[42:43]
	v_cvt_pk_bf16_f32 v42, v31, v44
	v_cvt_pk_bf16_f32 v43, v45, v74
	v_cvt_pk_bf16_f32 v44, v70, v71
	v_cvt_pk_bf16_f32 v45, v72, v73
	global_store_dwordx4 v[52:53], v[42:45], off
	v_mul_f32_e32 v31, v32, v0
	v_mul_f32_e32 v32, v33, v0
	v_mul_f32_e32 v43, v49, v0
	v_mul_f32_e32 v44, v50, v0
	v_mul_f32_e32 v45, v51, v0
	v_mul_f32_e32 v33, v48, v0
	v_mul_f32_e32 v46, v46, v0
	v_mul_f32_e32 v0, v47, v0
	v_cvt_pk_bf16_f32 v42, v31, v32
	v_cvt_pk_bf16_f32 v43, v33, v43
	v_cvt_pk_bf16_f32 v44, v44, v45
	v_cvt_pk_bf16_f32 v45, v46, v0
	global_store_dwordx4 v[52:53], v[42:45], off offset:64
